# GEMM MMA blocks: MFMAs re-ordered in snake order so consecutive MFMAs share one operand (all four GEMM loops)
# baseline (speedup 1.0000x reference)
; #define PG8_STAGE(bufoff, gbase, voff) do { _Pragma("unroll") for (int _i = 0; _i < 2; ++_i) \
;         __builtin_amdgcn_global_load_lds((const unsigned*)((const char*)(gbase) + (voff)[_i]), (LAS unsigned*)(lds + (bufoff) + ldsw + _i * 8192), 16, 0, 0); } while (0)
; #define PG8_LDA(dst, b, h) do { _Pragma("unroll") for (int m = 0; m < 4; ++m) _Pragma("unroll") for (int k = 0; k < 2; ++k) dst[m][k] = *(const LAS bf16x8*)(lds + PG8_SA(b, h) + aoff + m * 2048 + k * 1024); } while (0)
; #define PG8_LDB(dst, b, h) do { _Pragma("unroll") for (int n = 0; n < 2; ++n) _Pragma("unroll") for (int k = 0; k < 2; ++k) dst[n][k] = *(const LAS bf16x8*)(lds + PG8_SB(b, h) + boff + n * 2048 + k * 1024); } while (0)
; #define PG8_MMA(ai, bj, At, Bt) do { __builtin_amdgcn_s_setprio(1); _Pragma("unroll") for (int m = 0; m < 4; ++m) _Pragma("unroll") for (int n = 0; n < 2; ++n) _Pragma("unroll") for (int k = 0; k < 2; ++k) \
;         acc[ai][bj][m][n] = __builtin_amdgcn_mfma_f32_16x16x32_bf16(Bt[n][k], At[m][k], acc[ai][bj][m][n], 0, 0, 0); __builtin_amdgcn_s_setprio(0); } while (0)
; #define PG8_WAIT_V(n) asm volatile("s_waitcnt vmcnt(" #n ")" ::: "memory")
; #define PG8_WAIT_L(n) asm volatile("s_waitcnt lgkmcnt(" #n ")" ::: "memory")
; #define PG8_BAR __builtin_amdgcn_s_barrier()
; #define PG8_SCHED __builtin_amdgcn_sched_barrier(0)
; template <class Epi, class Ptrs>
; __device__ __forceinline__ void gemm_phase(LAS unsigned char* lds, const int K, const StaticOrder& S, const Ptrs& P, const Epi& E) {
;     ...
;             PG8_LDB(B0, 0, 0); PG8_SCHED; PG8_LDA(At, 0, 0); PG8_STAGE(PG8_SA(1, 1), a1 + hstep, voffA);
;             PG8_WAIT_L(8); PG8_BAR; PG8_WAIT_L(0); PG8_MMA(0, 0, At, B0); PG8_BAR; PG8_SCHED;
;             PG8_LDB(B1, 0, 1); PG8_STAGE(PG8_SB(0, 0), b2, voffB);
;             PG8_BAR; PG8_WAIT_L(0); PG8_MMA(0, 1, At, B1); PG8_BAR;
;             PG8_LDA(At, 0, 1); PG8_STAGE(PG8_SA(0, 0), a2, voffA);
;             PG8_BAR; PG8_WAIT_L(0); PG8_MMA(1, 0, At, B0); PG8_BAR; PG8_SCHED;
;             PG8_STAGE(PG8_SB(0, 1), b2 + hstep, voffB);
;             PG8_WAIT_V(6); PG8_BAR; PG8_MMA(1, 1, At, B1); PG8_BAR;
.LBB0_127:
	ds_read_b128 v[150:153], v205
	ds_read_b128 v[154:157], v205 offset:1024
	ds_read_b128 v[158:161], v205 offset:2048
	ds_read_b128 v[162:165], v205 offset:3072
	s_add_u32 s69, s6, 0xfffc0080
	s_addc_u32 s71, s7, -1
	s_cmp_eq_u32 s63, 12
	s_cselect_b32 s81, s1, s71
	s_cselect_b32 s80, s0, s69
	s_cselect_b32 s79, s73, s25
	s_cselect_b32 s78, s72, s20
	v_lshl_add_u64 v[198:199], s[6:7], 0, v[142:143]
	s_add_i32 m0, s67, 0xc000
	ds_read_b128 v[166:169], v206
	ds_read_b128 v[170:173], v206 offset:1024
	ds_read_b128 v[174:177], v206 offset:2048
	ds_read_b128 v[178:181], v206 offset:3072
	ds_read_b128 v[182:185], v206 offset:4096
	ds_read_b128 v[186:189], v206 offset:5120
	ds_read_b128 v[190:193], v206 offset:6144
	ds_read_b128 v[194:197], v206 offset:7168
	global_load_lds_dwordx4 v[198:199], off
	v_lshl_add_u64 v[198:199], s[6:7], 0, v[144:145]
	s_add_i32 m0, s67, 0xe000
	s_nop 0
	global_load_lds_dwordx4 v[198:199], off
	s_waitcnt lgkmcnt(8)
	s_barrier
	s_waitcnt lgkmcnt(0)
	s_setprio 1
	s_waitcnt lgkmcnt(0)
	v_mfma_f32_16x16x32_bf16 v[120:123], v[150:153], v[166:169], v[120:123]
	v_mfma_f32_16x16x32_bf16 v[116:119], v[158:161], v[166:169], v[116:119]
	v_mfma_f32_16x16x32_bf16 v[100:103], v[158:161], v[174:177], v[100:103]
	v_mfma_f32_16x16x32_bf16 v[104:107], v[150:153], v[174:177], v[104:107]
	v_mfma_f32_16x16x32_bf16 v[88:91], v[150:153], v[182:185], v[88:91]
	v_mfma_f32_16x16x32_bf16 v[84:87], v[158:161], v[182:185], v[84:87]
	v_mfma_f32_16x16x32_bf16 v[68:71], v[158:161], v[190:193], v[68:71]
	v_mfma_f32_16x16x32_bf16 v[72:75], v[150:153], v[190:193], v[72:75]
	v_mfma_f32_16x16x32_bf16 v[120:123], v[154:157], v[170:173], v[120:123]
	v_mfma_f32_16x16x32_bf16 v[116:119], v[162:165], v[170:173], v[116:119]
	v_mfma_f32_16x16x32_bf16 v[100:103], v[162:165], v[178:181], v[100:103]
	v_mfma_f32_16x16x32_bf16 v[104:107], v[154:157], v[178:181], v[104:107]
	v_mfma_f32_16x16x32_bf16 v[88:91], v[154:157], v[186:189], v[88:91]
	v_mfma_f32_16x16x32_bf16 v[84:87], v[162:165], v[186:189], v[84:87]
	v_mfma_f32_16x16x32_bf16 v[68:71], v[162:165], v[194:197], v[68:71]
	v_mfma_f32_16x16x32_bf16 v[72:75], v[154:157], v[194:197], v[72:75]
	s_setprio 0
	s_barrier
	s_add_i32 s69, s91, s65
	v_lshl_add_u64 v[202:203], s[78:79], 0, v[134:135]
	s_mov_b32 m0, s69
	ds_read_b128 v[198:201], v207
	ds_read_b128 v[210:213], v207 offset:1024
	ds_read_b128 v[214:217], v207 offset:2048
	ds_read_b128 v[218:221], v207 offset:3072
	global_load_lds_dwordx4 v[202:203], off
	v_lshl_add_u64 v[222:223], s[78:79], 0, v[138:139]
	s_add_i32 m0, s69, 0x2000
	s_nop 0
	global_load_lds_dwordx4 v[222:223], off
	s_barrier
	s_waitcnt lgkmcnt(0)
	s_setprio 1
	s_waitcnt lgkmcnt(0)
	v_mfma_f32_16x16x32_bf16 v[124:127], v[198:201], v[166:169], v[124:127]
	v_mfma_f32_16x16x32_bf16 v[112:115], v[214:217], v[166:169], v[112:115]
	v_mfma_f32_16x16x32_bf16 v[96:99], v[214:217], v[174:177], v[96:99]
	v_mfma_f32_16x16x32_bf16 v[108:111], v[198:201], v[174:177], v[108:111]
	v_mfma_f32_16x16x32_bf16 v[92:95], v[198:201], v[182:185], v[92:95]
	v_mfma_f32_16x16x32_bf16 v[80:83], v[214:217], v[182:185], v[80:83]
	v_mfma_f32_16x16x32_bf16 v[64:67], v[214:217], v[190:193], v[64:67]
	v_mfma_f32_16x16x32_bf16 v[76:79], v[198:201], v[190:193], v[76:79]
	v_mfma_f32_16x16x32_bf16 v[124:127], v[210:213], v[170:173], v[124:127]
	v_mfma_f32_16x16x32_bf16 v[112:115], v[218:221], v[170:173], v[112:115]
	v_mfma_f32_16x16x32_bf16 v[96:99], v[218:221], v[178:181], v[96:99]
	v_mfma_f32_16x16x32_bf16 v[108:111], v[210:213], v[178:181], v[108:111]
	v_mfma_f32_16x16x32_bf16 v[92:95], v[210:213], v[186:189], v[92:95]
	v_mfma_f32_16x16x32_bf16 v[80:83], v[218:221], v[186:189], v[80:83]
	v_mfma_f32_16x16x32_bf16 v[64:67], v[218:221], v[194:197], v[64:67]
	v_mfma_f32_16x16x32_bf16 v[76:79], v[210:213], v[194:197], v[76:79]
	s_setprio 0
	s_mov_b32 m0, s67
	v_lshl_add_u64 v[224:225], s[80:81], 0, v[132:133]
	s_barrier
	ds_read_b128 v[166:169], v206 offset:16384
	ds_read_b128 v[170:173], v206 offset:17408
	ds_read_b128 v[174:177], v206 offset:18432
	ds_read_b128 v[178:181], v206 offset:19456
	ds_read_b128 v[182:185], v206 offset:20480
	ds_read_b128 v[186:189], v206 offset:21504
	ds_read_b128 v[190:193], v206 offset:22528
	ds_read_b128 v[194:197], v206 offset:23552
	global_load_lds_dwordx4 v[224:225], off
	v_lshl_add_u64 v[226:227], s[80:81], 0, v[136:137]
	s_mov_b32 m0, s75
	s_nop 0
	global_load_lds_dwordx4 v[226:227], off
	s_barrier
	s_waitcnt lgkmcnt(0)
	s_setprio 1
	s_waitcnt lgkmcnt(0)
	v_mfma_f32_16x16x32_bf16 v[56:59], v[150:153], v[166:169], v[56:59]
	v_mfma_f32_16x16x32_bf16 v[52:55], v[158:161], v[166:169], v[52:55]
	v_mfma_f32_16x16x32_bf16 v[36:39], v[158:161], v[174:177], v[36:39]
	v_mfma_f32_16x16x32_bf16 v[40:43], v[150:153], v[174:177], v[40:43]
	v_mfma_f32_16x16x32_bf16 v[24:27], v[150:153], v[182:185], v[24:27]
	v_mfma_f32_16x16x32_bf16 v[20:23], v[158:161], v[182:185], v[20:23]
	v_mfma_f32_16x16x32_bf16 v[4:7], v[158:161], v[190:193], v[4:7]
	v_mfma_f32_16x16x32_bf16 v[8:11], v[150:153], v[190:193], v[8:11]
	v_mfma_f32_16x16x32_bf16 v[56:59], v[154:157], v[170:173], v[56:59]
	v_mfma_f32_16x16x32_bf16 v[52:55], v[162:165], v[170:173], v[52:55]
	v_mfma_f32_16x16x32_bf16 v[36:39], v[162:165], v[178:181], v[36:39]
	v_mfma_f32_16x16x32_bf16 v[40:43], v[154:157], v[178:181], v[40:43]
	v_mfma_f32_16x16x32_bf16 v[24:27], v[154:157], v[186:189], v[24:27]
	v_mfma_f32_16x16x32_bf16 v[20:23], v[162:165], v[186:189], v[20:23]
	v_mfma_f32_16x16x32_bf16 v[4:7], v[162:165], v[194:197], v[4:7]
	v_mfma_f32_16x16x32_bf16 v[8:11], v[154:157], v[194:197], v[8:11]
	s_setprio 0
	s_barrier
; #define PG8_STAGE(bufoff, gbase, voff) do { _Pragma("unroll") for (int _i = 0; _i < 2; ++_i) \
;         __builtin_amdgcn_global_load_lds((const unsigned*)((const char*)(gbase) + (voff)[_i]), (LAS unsigned*)(lds + (bufoff) + ldsw + _i * 8192), 16, 0, 0); } while (0)
; #define PG8_LDA(dst, b, h) do { _Pragma("unroll") for (int m = 0; m < 4; ++m) _Pragma("unroll") for (int k = 0; k < 2; ++k) dst[m][k] = *(const LAS bf16x8*)(lds + PG8_SA(b, h) + aoff + m * 2048 + k * 1024); } while (0)
; #define PG8_LDB(dst, b, h) do { _Pragma("unroll") for (int n = 0; n < 2; ++n) _Pragma("unroll") for (int k = 0; k < 2; ++k) dst[n][k] = *(const LAS bf16x8*)(lds + PG8_SB(b, h) + boff + n * 2048 + k * 1024); } while (0)
; #define PG8_MMA(ai, bj, At, Bt) do { __builtin_amdgcn_s_setprio(1); _Pragma("unroll") for (int m = 0; m < 4; ++m) _Pragma("unroll") for (int n = 0; n < 2; ++n) _Pragma("unroll") for (int k = 0; k < 2; ++k) \
;         acc[ai][bj][m][n] = __builtin_amdgcn_mfma_f32_16x16x32_bf16(Bt[n][k], At[m][k], acc[ai][bj][m][n], 0, 0, 0); __builtin_amdgcn_s_setprio(0); } while (0)
; #define PG8_WAIT_V(n) asm volatile("s_waitcnt vmcnt(" #n ")" ::: "memory")
; #define PG8_WAIT_L(n) asm volatile("s_waitcnt lgkmcnt(" #n ")" ::: "memory")
; #define PG8_BAR __builtin_amdgcn_s_barrier()
; #define PG8_SCHED __builtin_amdgcn_sched_barrier(0)
; template <class Epi, class Ptrs>
; __device__ __forceinline__ void gemm_phase(LAS unsigned char* lds, const int K, const StaticOrder& S, const Ptrs& P, const Epi& E) {
;     ...
;             PG8_WAIT_V(6); PG8_BAR; PG8_MMA(1, 1, At, B1); PG8_BAR;
;             PG8_LDB(B0, 1, 0); PG8_SCHED; PG8_LDA(At, 1, 0); PG8_STAGE(PG8_SA(0, 1), a2 + hstep, voffA);
;             PG8_WAIT_L(8); PG8_BAR; PG8_WAIT_L(0); PG8_MMA(0, 0, At, B0); PG8_BAR; PG8_SCHED;
;             PG8_LDB(B1, 1, 1); PG8_STAGE(PG8_SB(1, 0), b3, voffB);
;             PG8_BAR; PG8_WAIT_L(0); PG8_MMA(0, 1, At, B1); PG8_BAR;
;             PG8_LDA(At, 1, 1); PG8_STAGE(PG8_SA(1, 0), a3, voffA);
;             PG8_BAR; PG8_WAIT_L(0); PG8_MMA(1, 0, At, B0); PG8_BAR; PG8_SCHED;
	s_add_u32 s82, s78, 0x40000
	s_addc_u32 s83, s79, 0
	s_add_i32 s69, s92, s65
	v_lshl_add_u64 v[150:151], s[82:83], 0, v[134:135]
	s_mov_b32 m0, s69
	s_nop 0
	global_load_lds_dwordx4 v[150:151], off
	v_lshl_add_u64 v[150:151], s[82:83], 0, v[138:139]
	s_add_i32 m0, s69, 0x2000
	s_nop 0
	global_load_lds_dwordx4 v[150:151], off
	s_waitcnt vmcnt(6)
	s_barrier
	s_setprio 1
	v_mfma_f32_16x16x32_bf16 v[60:63], v[198:201], v[166:169], v[60:63]
	v_mfma_f32_16x16x32_bf16 v[48:51], v[214:217], v[166:169], v[48:51]
	v_mfma_f32_16x16x32_bf16 v[32:35], v[214:217], v[174:177], v[32:35]
	v_mfma_f32_16x16x32_bf16 v[44:47], v[198:201], v[174:177], v[44:47]
	v_mfma_f32_16x16x32_bf16 v[28:31], v[198:201], v[182:185], v[28:31]
	v_mfma_f32_16x16x32_bf16 v[16:19], v[214:217], v[182:185], v[16:19]
	v_mfma_f32_16x16x32_bf16 v[0:3], v[214:217], v[190:193], v[0:3]
	v_mfma_f32_16x16x32_bf16 v[12:15], v[198:201], v[190:193], v[12:15]
	v_mfma_f32_16x16x32_bf16 v[60:63], v[210:213], v[170:173], v[60:63]
	v_mfma_f32_16x16x32_bf16 v[48:51], v[218:221], v[170:173], v[48:51]
	v_mfma_f32_16x16x32_bf16 v[32:35], v[218:221], v[178:181], v[32:35]
	v_mfma_f32_16x16x32_bf16 v[44:47], v[210:213], v[178:181], v[44:47]
	v_mfma_f32_16x16x32_bf16 v[28:31], v[210:213], v[186:189], v[28:31]
	v_mfma_f32_16x16x32_bf16 v[16:19], v[218:221], v[186:189], v[16:19]
	v_mfma_f32_16x16x32_bf16 v[0:3], v[218:221], v[194:197], v[0:3]
	v_mfma_f32_16x16x32_bf16 v[12:15], v[210:213], v[194:197], v[12:15]
	s_setprio 0
	s_add_i32 s69, 0, 0x18000
	v_add_u32_e32 v140, s69, v131
	s_barrier
	ds_read_b128 v[150:153], v140
	ds_read_b128 v[154:157], v140 offset:1024
	ds_read_b128 v[158:161], v140 offset:2048
	ds_read_b128 v[162:165], v140 offset:3072
	s_add_u32 s80, s80, 0x40000
	s_addc_u32 s81, s81, 0
	s_mov_b32 m0, s77
	v_lshl_add_u64 v[198:199], s[80:81], 0, v[132:133]
	ds_read_b128 v[166:169], v206 offset:32768
	ds_read_b128 v[170:173], v206 offset:33792
	ds_read_b128 v[174:177], v206 offset:34816
	ds_read_b128 v[178:181], v206 offset:35840
	ds_read_b128 v[182:185], v206 offset:36864
	ds_read_b128 v[186:189], v206 offset:37888
	ds_read_b128 v[190:193], v206 offset:38912
	ds_read_b128 v[194:197], v206 offset:39936
	global_load_lds_dwordx4 v[198:199], off
	v_lshl_add_u64 v[198:199], s[80:81], 0, v[136:137]
	s_mov_b32 m0, s85
	s_nop 0
	global_load_lds_dwordx4 v[198:199], off
	s_waitcnt lgkmcnt(8)
	s_barrier
	s_waitcnt lgkmcnt(0)
	s_setprio 1
	s_waitcnt lgkmcnt(0)
	v_mfma_f32_16x16x32_bf16 v[120:123], v[150:153], v[166:169], v[120:123]
	v_mfma_f32_16x16x32_bf16 v[116:119], v[158:161], v[166:169], v[116:119]
	v_mfma_f32_16x16x32_bf16 v[100:103], v[158:161], v[174:177], v[100:103]
	v_mfma_f32_16x16x32_bf16 v[104:107], v[150:153], v[174:177], v[104:107]
	v_mfma_f32_16x16x32_bf16 v[88:91], v[150:153], v[182:185], v[88:91]
	v_mfma_f32_16x16x32_bf16 v[84:87], v[158:161], v[182:185], v[84:87]
	v_mfma_f32_16x16x32_bf16 v[68:71], v[158:161], v[190:193], v[68:71]
	v_mfma_f32_16x16x32_bf16 v[72:75], v[150:153], v[190:193], v[72:75]
	v_mfma_f32_16x16x32_bf16 v[120:123], v[154:157], v[170:173], v[120:123]
	v_mfma_f32_16x16x32_bf16 v[116:119], v[162:165], v[170:173], v[116:119]
	v_mfma_f32_16x16x32_bf16 v[100:103], v[162:165], v[178:181], v[100:103]
	v_mfma_f32_16x16x32_bf16 v[104:107], v[154:157], v[178:181], v[104:107]
	v_mfma_f32_16x16x32_bf16 v[88:91], v[154:157], v[186:189], v[88:91]
	v_mfma_f32_16x16x32_bf16 v[84:87], v[162:165], v[186:189], v[84:87]
	v_mfma_f32_16x16x32_bf16 v[68:71], v[162:165], v[194:197], v[68:71]
	v_mfma_f32_16x16x32_bf16 v[72:75], v[154:157], v[194:197], v[72:75]
	s_setprio 0
	s_barrier
	s_add_i32 s71, 0, 0x1c000
	s_add_i32 s69, s69, s65
	v_add_u32_e32 v140, s71, v131
	v_lshl_add_u64 v[202:203], v[202:203], 0, s[58:59]
	s_mov_b32 m0, s69
	ds_read_b128 v[198:201], v140
	ds_read_b128 v[210:213], v140 offset:1024
	ds_read_b128 v[214:217], v140 offset:2048
	ds_read_b128 v[218:221], v140 offset:3072
	global_load_lds_dwordx4 v[202:203], off
	v_lshl_add_u64 v[202:203], v[222:223], 0, s[58:59]
	s_add_i32 m0, s69, 0x2000
	s_nop 0
	global_load_lds_dwordx4 v[202:203], off
	s_barrier
; #define PG8_WAIT_V(n) asm volatile("s_waitcnt vmcnt(" #n ")" ::: "memory")
; template <class Epi, class Ptrs>
; __device__ __forceinline__ void gemm_phase(LAS unsigned char* lds, const int K, const StaticOrder& S, const Ptrs& P, const Epi& E) {
;     ...
;             PG8_BAR; PG8_WAIT_L(0); PG8_MMA(1, 0, At, B0); PG8_BAR; PG8_SCHED;
;             PG8_STAGE(PG8_SB(1, 1), b3 + hstep, voffB);
;             PG8_WAIT_V(6); PG8_BAR; PG8_MMA(1, 1, At, B1); PG8_BAR;
;         }
;         E(acc, cur, ui, wr, wc, fr, fq);
;     __device__ __forceinline__ void operator()(const f32x4 (&acc)[2][2][4][2], const Unit& u, int ui, int wr, int wc, int fr, int fq) const {
;     ...
;         if (pn < 8) {
;             bf16_t* base = (bf16_t*)(ws + WS_U) + (size_t)(u.pm * 256 + wr * 64 + fr) * DM + pn * 128 + wc * 32 + 8 * fq;
; #pragma unroll
;             for (int ai = 0; ai < 2; ++ai)
; #pragma unroll
;                 for (int m = 0; m < 4; ++m) {
;                     const f32x4 g0 = g1_4(acc[ai][0][m][0], acc[ai][1][m][0]), g1 = g1_4(acc[ai][0][m][1], acc[ai][1][m][1]);
;                     *(u32x4*)(base + (size_t)(ai * 128 + m * 16) * DM) = pack8(g0, g1); }
;             return; }
;         if (pn >= 17 && pn < 21) {
;             bf16_t* base = (bf16_t*)(dout + DO_GVT) + (size_t)((pn - 17) * 256 + wr * 64 + fr) * MTOK + u.pm * 256 + wc * 32 + 8 * fq;
;             float* pp = (float*)(ws + WS_PART) + (size_t)(u.pm * 256 + wc * 32 + 8 * fq) * 8 + (pn - 17) * 2 + wr;
; #pragma unroll
;             for (int bj = 0; bj < 2; ++bj) { f32x4 sq0 = {0.f, 0.f, 0.f, 0.f}, sq1 = {0.f, 0.f, 0.f, 0.f};
; #pragma unroll
;                 for (int ai = 0; ai < 2; ++ai)
; #pragma unroll
;                     for (int m = 0; m < 4; ++m) { const f32x4 g0 = gelu4(acc[ai][bj][m][0]), g1 = gelu4(acc[ai][bj][m][1]);
;                         sq0 += g0 * g0; sq1 += g1 * g1;
;                         *(u32x4*)(base + (size_t)(ai * 128 + m * 16) * MTOK + bj * 128) = pack8(g0, g1); }
; #pragma unroll
;                 for (int j = 0; j < 4; ++j) { const float t0 = row16_sum(sq0[j]), t1 = row16_sum(sq1[j]); if (fr == 0) { pp[(size_t)(bj * 128 + j) * 8] = t0; pp[(size_t)(bj * 128 + 4 + j) * 8] = t1; } } }
;             return; }
;         bf16_t* base; size_t ld; int row0, col0, act;
;         if (pn < 12)      { base = (bf16_t*)(ws + WS_Q);  ld = DM;  row0 = u.pm * 256; col0 = (pn - 8) * 256;  act = 0; }
	s_waitcnt lgkmcnt(0)
	s_setprio 1
	s_waitcnt lgkmcnt(0)
	v_mfma_f32_16x16x32_bf16 v[124:127], v[198:201], v[166:169], v[124:127]
	v_mfma_f32_16x16x32_bf16 v[112:115], v[214:217], v[166:169], v[112:115]
	v_mfma_f32_16x16x32_bf16 v[96:99], v[214:217], v[174:177], v[96:99]
	v_mfma_f32_16x16x32_bf16 v[108:111], v[198:201], v[174:177], v[108:111]
	v_mfma_f32_16x16x32_bf16 v[92:95], v[198:201], v[182:185], v[92:95]
	v_mfma_f32_16x16x32_bf16 v[80:83], v[214:217], v[182:185], v[80:83]
	v_mfma_f32_16x16x32_bf16 v[64:67], v[214:217], v[190:193], v[64:67]
	v_mfma_f32_16x16x32_bf16 v[76:79], v[198:201], v[190:193], v[76:79]
	v_mfma_f32_16x16x32_bf16 v[124:127], v[210:213], v[170:173], v[124:127]
	v_mfma_f32_16x16x32_bf16 v[112:115], v[218:221], v[170:173], v[112:115]
	v_mfma_f32_16x16x32_bf16 v[96:99], v[218:221], v[178:181], v[96:99]
	v_mfma_f32_16x16x32_bf16 v[108:111], v[210:213], v[178:181], v[108:111]
	v_mfma_f32_16x16x32_bf16 v[92:95], v[210:213], v[186:189], v[92:95]
	v_mfma_f32_16x16x32_bf16 v[80:83], v[218:221], v[186:189], v[80:83]
	v_mfma_f32_16x16x32_bf16 v[64:67], v[218:221], v[194:197], v[64:67]
	v_mfma_f32_16x16x32_bf16 v[76:79], v[210:213], v[194:197], v[76:79]
	s_setprio 0
	s_mov_b32 m0, s89
	v_lshl_add_u64 v[202:203], v[224:225], 0, s[58:59]
	s_barrier
	ds_read_b128 v[166:169], v206 offset:49152
	ds_read_b128 v[170:173], v206 offset:50176
	ds_read_b128 v[174:177], v206 offset:51200
	ds_read_b128 v[178:181], v206 offset:52224
	ds_read_b128 v[182:185], v206 offset:53248
	ds_read_b128 v[186:189], v206 offset:54272
	ds_read_b128 v[190:193], v206 offset:55296
	ds_read_b128 v[194:197], v206 offset:56320
	global_load_lds_dwordx4 v[202:203], off
	v_lshl_add_u64 v[202:203], v[226:227], 0, s[58:59]
	s_mov_b32 m0, s90
	s_nop 0
	global_load_lds_dwordx4 v[202:203], off
	s_barrier
	s_waitcnt lgkmcnt(0)
	s_setprio 1
	s_waitcnt lgkmcnt(0)
	v_mfma_f32_16x16x32_bf16 v[56:59], v[150:153], v[166:169], v[56:59]
	v_mfma_f32_16x16x32_bf16 v[52:55], v[158:161], v[166:169], v[52:55]
	v_mfma_f32_16x16x32_bf16 v[36:39], v[158:161], v[174:177], v[36:39]
	v_mfma_f32_16x16x32_bf16 v[40:43], v[150:153], v[174:177], v[40:43]
	v_mfma_f32_16x16x32_bf16 v[24:27], v[150:153], v[182:185], v[24:27]
	v_mfma_f32_16x16x32_bf16 v[20:23], v[158:161], v[182:185], v[20:23]
	v_mfma_f32_16x16x32_bf16 v[4:7], v[158:161], v[190:193], v[4:7]
	v_mfma_f32_16x16x32_bf16 v[8:11], v[150:153], v[190:193], v[8:11]
	v_mfma_f32_16x16x32_bf16 v[56:59], v[154:157], v[170:173], v[56:59]
	v_mfma_f32_16x16x32_bf16 v[52:55], v[162:165], v[170:173], v[52:55]
	v_mfma_f32_16x16x32_bf16 v[36:39], v[162:165], v[178:181], v[36:39]
	v_mfma_f32_16x16x32_bf16 v[40:43], v[154:157], v[178:181], v[40:43]
	v_mfma_f32_16x16x32_bf16 v[24:27], v[154:157], v[186:189], v[24:27]
	v_mfma_f32_16x16x32_bf16 v[20:23], v[162:165], v[186:189], v[20:23]
	v_mfma_f32_16x16x32_bf16 v[4:7], v[162:165], v[194:197], v[4:7]
	v_mfma_f32_16x16x32_bf16 v[8:11], v[154:157], v[194:197], v[8:11]
	s_setprio 0
	s_barrier
	s_add_u32 s78, s78, 0x40080
	s_addc_u32 s79, s79, 0
	s_add_i32 s69, s71, s65
	v_lshl_add_u64 v[150:151], s[78:79], 0, v[134:135]
	s_mov_b32 m0, s69
	s_nop 0
	global_load_lds_dwordx4 v[150:151], off
	v_lshl_add_u64 v[150:151], s[78:79], 0, v[138:139]
	s_add_i32 m0, s69, 0x2000
	s_nop 0
	global_load_lds_dwordx4 v[150:151], off
	s_waitcnt vmcnt(6)
	s_barrier
	s_setprio 1
	v_mfma_f32_16x16x32_bf16 v[60:63], v[198:201], v[166:169], v[60:63]
	v_mfma_f32_16x16x32_bf16 v[48:51], v[214:217], v[166:169], v[48:51]
	v_mfma_f32_16x16x32_bf16 v[32:35], v[214:217], v[174:177], v[32:35]
	v_mfma_f32_16x16x32_bf16 v[44:47], v[198:201], v[174:177], v[44:47]
	v_mfma_f32_16x16x32_bf16 v[28:31], v[198:201], v[182:185], v[28:31]
	v_mfma_f32_16x16x32_bf16 v[16:19], v[214:217], v[182:185], v[16:19]
	v_mfma_f32_16x16x32_bf16 v[0:3], v[214:217], v[190:193], v[0:3]
	v_mfma_f32_16x16x32_bf16 v[12:15], v[198:201], v[190:193], v[12:15]
	v_mfma_f32_16x16x32_bf16 v[60:63], v[210:213], v[170:173], v[60:63]
	v_mfma_f32_16x16x32_bf16 v[48:51], v[218:221], v[170:173], v[48:51]
	v_mfma_f32_16x16x32_bf16 v[32:35], v[218:221], v[178:181], v[32:35]
	v_mfma_f32_16x16x32_bf16 v[44:47], v[210:213], v[178:181], v[44:47]
	v_mfma_f32_16x16x32_bf16 v[28:31], v[210:213], v[186:189], v[28:31]
	v_mfma_f32_16x16x32_bf16 v[16:19], v[218:221], v[186:189], v[16:19]
	v_mfma_f32_16x16x32_bf16 v[0:3], v[218:221], v[194:197], v[0:3]
	v_mfma_f32_16x16x32_bf16 v[12:15], v[210:213], v[194:197], v[12:15]
	s_setprio 0
	s_add_i32 s63, s63, 2
	s_add_u32 s6, s6, 0x100
	s_addc_u32 s7, s7, 0
	s_add_u32 s20, s20, 0x100
	s_addc_u32 s25, s25, 0
	s_cmp_gt_u32 s63, 13
	s_barrier
	s_cbranch_scc0 .LBB0_127
	s_cmp_gt_i32 s74, 7
	s_mov_b64 s[6:7], -1
	s_cbranch_scc0 .LBB0_188
	s_sub_i32 s25, s74, 17
	s_cmp_gt_u32 s25, 3
	s_cbranch_scc0 .LBB0_170
	s_lshl_b32 s69, s76, 8
	s_cmp_gt_u32 s74, 11
	s_cbranch_scc0 .LBB0_135
	s_cmp_eq_u32 s74, 12
	s_mov_b64 s[6:7], 0
	s_cbranch_scc1 .LBB0_134
	s_cmp_gt_u32 s74, 16
	s_cbranch_scc1 .LBB0_191
	s_lshl_b32 s20, s74, 8
	v_readlane_b32 s80, v254, 2
	s_addk_i32 s20, 0xf300
	s_mov_b64 s[78:79], 0x400
	s_mov_b64 s[82:83], -1
	s_mov_b32 s63, s69
	v_readlane_b32 s81, v254, 3
	s_andn2_b64 vcc, exec, s[6:7]
	s_cbranch_vccz .LBB0_136
	s_branch .LBB0_137

; #define PG8_STAGE(bufoff, gbase, voff) do { _Pragma("unroll") for (int _i = 0; _i < 2; ++_i) \
;         __builtin_amdgcn_global_load_lds((const unsigned*)((const char*)(gbase) + (voff)[_i]), (LAS unsigned*)(lds + (bufoff) + ldsw + _i * 8192), 16, 0, 0); } while (0)
; #define PG8_LDA(dst, b, h) do { _Pragma("unroll") for (int m = 0; m < 4; ++m) _Pragma("unroll") for (int k = 0; k < 2; ++k) dst[m][k] = *(const LAS bf16x8*)(lds + PG8_SA(b, h) + aoff + m * 2048 + k * 1024); } while (0)
; #define PG8_LDB(dst, b, h) do { _Pragma("unroll") for (int n = 0; n < 2; ++n) _Pragma("unroll") for (int k = 0; k < 2; ++k) dst[n][k] = *(const LAS bf16x8*)(lds + PG8_SB(b, h) + boff + n * 2048 + k * 1024); } while (0)
; #define PG8_MMA(ai, bj, At, Bt) do { __builtin_amdgcn_s_setprio(1); _Pragma("unroll") for (int m = 0; m < 4; ++m) _Pragma("unroll") for (int n = 0; n < 2; ++n) _Pragma("unroll") for (int k = 0; k < 2; ++k) \
;         acc[ai][bj][m][n] = __builtin_amdgcn_mfma_f32_16x16x32_bf16(Bt[n][k], At[m][k], acc[ai][bj][m][n], 0, 0, 0); __builtin_amdgcn_s_setprio(0); } while (0)
; #define PG8_WAIT_V(n) asm volatile("s_waitcnt vmcnt(" #n ")" ::: "memory")
; #define PG8_WAIT_L(n) asm volatile("s_waitcnt lgkmcnt(" #n ")" ::: "memory")
; #define PG8_BAR __builtin_amdgcn_s_barrier()
; #define PG8_SCHED __builtin_amdgcn_sched_barrier(0)
; template <class Epi, class Ptrs>
; __device__ __forceinline__ void gemm_phase(LAS unsigned char* lds, const int K, const StaticOrder& S, const Ptrs& P, const Epi& E) {
;     ...
;             PG8_LDB(B0, 0, 0); PG8_SCHED; PG8_LDA(At, 0, 0); PG8_STAGE(PG8_SA(1, 1), a1 + hstep, voffA);
;             PG8_WAIT_L(8); PG8_BAR; PG8_WAIT_L(0); PG8_MMA(0, 0, At, B0); PG8_BAR; PG8_SCHED;
;             PG8_LDB(B1, 0, 1); PG8_STAGE(PG8_SB(0, 0), b2, voffB);
;             PG8_BAR; PG8_WAIT_L(0); PG8_MMA(0, 1, At, B1); PG8_BAR;
;             PG8_LDA(At, 0, 1); PG8_STAGE(PG8_SA(0, 0), a2, voffA);
;             PG8_BAR; PG8_WAIT_L(0); PG8_MMA(1, 0, At, B0); PG8_BAR; PG8_SCHED;
;             PG8_STAGE(PG8_SB(0, 1), b2 + hstep, voffB);
;             PG8_WAIT_V(6); PG8_BAR; PG8_MMA(1, 1, At, B1); PG8_BAR;
.LBB0_353:
	ds_read_b128 v[128:131], v207
	ds_read_b128 v[132:135], v207 offset:1024
	ds_read_b128 v[136:139], v207 offset:2048
	ds_read_b128 v[140:143], v207 offset:3072
	s_add_u32 s42, s38, 0xfffc0080
	s_addc_u32 s43, s39, -1
	s_cmp_eq_u32 s41, 12
	s_cselect_b32 s45, s1, s43
	s_cselect_b32 s44, s0, s42
	s_cselect_b32 s43, s25, s23
	s_cselect_b32 s42, s24, s21
	v_lshl_add_u64 v[192:193], s[38:39], 0, v[184:185]
	s_add_i32 m0, s54, 0xc000
	ds_read_b128 v[144:147], v209
	ds_read_b128 v[148:151], v209 offset:1024
	ds_read_b128 v[152:155], v209 offset:2048
	ds_read_b128 v[156:159], v209 offset:3072
	ds_read_b128 v[160:163], v209 offset:4096
	ds_read_b128 v[164:167], v209 offset:5120
	ds_read_b128 v[168:171], v209 offset:6144
	ds_read_b128 v[172:175], v209 offset:7168
	global_load_lds_dwordx4 v[192:193], off
	v_lshl_add_u64 v[192:193], s[38:39], 0, v[186:187]
	s_add_i32 m0, s54, 0xe000
	s_nop 0
	global_load_lds_dwordx4 v[192:193], off
	s_waitcnt lgkmcnt(8)
	s_barrier
	s_waitcnt lgkmcnt(0)
	s_setprio 1
	s_waitcnt lgkmcnt(0)
	v_mfma_f32_16x16x32_bf16 v[124:127], v[128:131], v[144:147], v[124:127]
	v_mfma_f32_16x16x32_bf16 v[120:123], v[136:139], v[144:147], v[120:123]
	v_mfma_f32_16x16x32_bf16 v[104:107], v[136:139], v[152:155], v[104:107]
	v_mfma_f32_16x16x32_bf16 v[108:111], v[128:131], v[152:155], v[108:111]
	v_mfma_f32_16x16x32_bf16 v[92:95], v[128:131], v[160:163], v[92:95]
	v_mfma_f32_16x16x32_bf16 v[88:91], v[136:139], v[160:163], v[88:91]
	v_mfma_f32_16x16x32_bf16 v[72:75], v[136:139], v[168:171], v[72:75]
	v_mfma_f32_16x16x32_bf16 v[76:79], v[128:131], v[168:171], v[76:79]
	v_mfma_f32_16x16x32_bf16 v[124:127], v[132:135], v[148:151], v[124:127]
	v_mfma_f32_16x16x32_bf16 v[120:123], v[140:143], v[148:151], v[120:123]
	v_mfma_f32_16x16x32_bf16 v[104:107], v[140:143], v[156:159], v[104:107]
	v_mfma_f32_16x16x32_bf16 v[108:111], v[132:135], v[156:159], v[108:111]
	v_mfma_f32_16x16x32_bf16 v[92:95], v[132:135], v[164:167], v[92:95]
	v_mfma_f32_16x16x32_bf16 v[88:91], v[140:143], v[164:167], v[88:91]
	v_mfma_f32_16x16x32_bf16 v[72:75], v[140:143], v[172:175], v[72:75]
	v_mfma_f32_16x16x32_bf16 v[76:79], v[132:135], v[172:175], v[76:79]
	s_setprio 0
	s_barrier
	s_add_i32 s69, s66, s51
	v_lshl_add_u64 v[216:217], s[42:43], 0, v[178:179]
	s_mov_b32 m0, s69
	ds_read_b128 v[192:195], v210
	ds_read_b128 v[196:199], v210 offset:1024
	ds_read_b128 v[200:203], v210 offset:2048
	ds_read_b128 v[212:215], v210 offset:3072
	global_load_lds_dwordx4 v[216:217], off
	v_lshl_add_u64 v[218:219], s[42:43], 0, v[182:183]
	s_add_i32 m0, s69, 0x2000
	s_nop 0
	global_load_lds_dwordx4 v[218:219], off
	s_barrier
	s_waitcnt lgkmcnt(0)
	s_setprio 1
	s_waitcnt lgkmcnt(0)
	v_mfma_f32_16x16x32_bf16 v[116:119], v[192:195], v[144:147], v[116:119]
	v_mfma_f32_16x16x32_bf16 v[112:115], v[200:203], v[144:147], v[112:115]
	v_mfma_f32_16x16x32_bf16 v[96:99], v[200:203], v[152:155], v[96:99]
	v_mfma_f32_16x16x32_bf16 v[100:103], v[192:195], v[152:155], v[100:103]
	v_mfma_f32_16x16x32_bf16 v[84:87], v[192:195], v[160:163], v[84:87]
	v_mfma_f32_16x16x32_bf16 v[80:83], v[200:203], v[160:163], v[80:83]
	v_mfma_f32_16x16x32_bf16 v[64:67], v[200:203], v[168:171], v[64:67]
	v_mfma_f32_16x16x32_bf16 v[68:71], v[192:195], v[168:171], v[68:71]
	v_mfma_f32_16x16x32_bf16 v[116:119], v[196:199], v[148:151], v[116:119]
	v_mfma_f32_16x16x32_bf16 v[112:115], v[212:215], v[148:151], v[112:115]
	v_mfma_f32_16x16x32_bf16 v[96:99], v[212:215], v[156:159], v[96:99]
	v_mfma_f32_16x16x32_bf16 v[100:103], v[196:199], v[156:159], v[100:103]
	v_mfma_f32_16x16x32_bf16 v[84:87], v[196:199], v[164:167], v[84:87]
	v_mfma_f32_16x16x32_bf16 v[80:83], v[212:215], v[164:167], v[80:83]
	v_mfma_f32_16x16x32_bf16 v[64:67], v[212:215], v[172:175], v[64:67]
	v_mfma_f32_16x16x32_bf16 v[68:71], v[196:199], v[172:175], v[68:71]
	s_setprio 0
	s_mov_b32 m0, s54
	v_lshl_add_u64 v[220:221], s[44:45], 0, v[176:177]
	s_barrier
	ds_read_b128 v[144:147], v209 offset:16384
	ds_read_b128 v[148:151], v209 offset:17408
	ds_read_b128 v[152:155], v209 offset:18432
	ds_read_b128 v[156:159], v209 offset:19456
	ds_read_b128 v[160:163], v209 offset:20480
	ds_read_b128 v[164:167], v209 offset:21504
	ds_read_b128 v[168:171], v209 offset:22528
	ds_read_b128 v[172:175], v209 offset:23552
	global_load_lds_dwordx4 v[220:221], off
	v_lshl_add_u64 v[222:223], s[44:45], 0, v[180:181]
	s_mov_b32 m0, s55
	s_nop 0
	global_load_lds_dwordx4 v[222:223], off
	s_barrier
	s_waitcnt lgkmcnt(0)
	s_setprio 1
	s_waitcnt lgkmcnt(0)
	v_mfma_f32_16x16x32_bf16 v[60:63], v[128:131], v[144:147], v[60:63]
	v_mfma_f32_16x16x32_bf16 v[56:59], v[136:139], v[144:147], v[56:59]
	v_mfma_f32_16x16x32_bf16 v[40:43], v[136:139], v[152:155], v[40:43]
	v_mfma_f32_16x16x32_bf16 v[44:47], v[128:131], v[152:155], v[44:47]
	v_mfma_f32_16x16x32_bf16 v[28:31], v[128:131], v[160:163], v[28:31]
	v_mfma_f32_16x16x32_bf16 v[24:27], v[136:139], v[160:163], v[24:27]
	v_mfma_f32_16x16x32_bf16 v[8:11], v[136:139], v[168:171], v[8:11]
	v_mfma_f32_16x16x32_bf16 v[12:15], v[128:131], v[168:171], v[12:15]
	v_mfma_f32_16x16x32_bf16 v[60:63], v[132:135], v[148:151], v[60:63]
	v_mfma_f32_16x16x32_bf16 v[56:59], v[140:143], v[148:151], v[56:59]
	v_mfma_f32_16x16x32_bf16 v[40:43], v[140:143], v[156:159], v[40:43]
	v_mfma_f32_16x16x32_bf16 v[44:47], v[132:135], v[156:159], v[44:47]
	v_mfma_f32_16x16x32_bf16 v[28:31], v[132:135], v[164:167], v[28:31]
	v_mfma_f32_16x16x32_bf16 v[24:27], v[140:143], v[164:167], v[24:27]
	v_mfma_f32_16x16x32_bf16 v[8:11], v[140:143], v[172:175], v[8:11]
	v_mfma_f32_16x16x32_bf16 v[12:15], v[132:135], v[172:175], v[12:15]
	s_setprio 0
	s_barrier
; #define PG8_STAGE(bufoff, gbase, voff) do { _Pragma("unroll") for (int _i = 0; _i < 2; ++_i) \
;         __builtin_amdgcn_global_load_lds((const unsigned*)((const char*)(gbase) + (voff)[_i]), (LAS unsigned*)(lds + (bufoff) + ldsw + _i * 8192), 16, 0, 0); } while (0)
; #define PG8_LDA(dst, b, h) do { _Pragma("unroll") for (int m = 0; m < 4; ++m) _Pragma("unroll") for (int k = 0; k < 2; ++k) dst[m][k] = *(const LAS bf16x8*)(lds + PG8_SA(b, h) + aoff + m * 2048 + k * 1024); } while (0)
; #define PG8_LDB(dst, b, h) do { _Pragma("unroll") for (int n = 0; n < 2; ++n) _Pragma("unroll") for (int k = 0; k < 2; ++k) dst[n][k] = *(const LAS bf16x8*)(lds + PG8_SB(b, h) + boff + n * 2048 + k * 1024); } while (0)
; #define PG8_MMA(ai, bj, At, Bt) do { __builtin_amdgcn_s_setprio(1); _Pragma("unroll") for (int m = 0; m < 4; ++m) _Pragma("unroll") for (int n = 0; n < 2; ++n) _Pragma("unroll") for (int k = 0; k < 2; ++k) \
;         acc[ai][bj][m][n] = __builtin_amdgcn_mfma_f32_16x16x32_bf16(Bt[n][k], At[m][k], acc[ai][bj][m][n], 0, 0, 0); __builtin_amdgcn_s_setprio(0); } while (0)
; #define PG8_WAIT_V(n) asm volatile("s_waitcnt vmcnt(" #n ")" ::: "memory")
; #define PG8_WAIT_L(n) asm volatile("s_waitcnt lgkmcnt(" #n ")" ::: "memory")
; #define PG8_BAR __builtin_amdgcn_s_barrier()
; #define PG8_SCHED __builtin_amdgcn_sched_barrier(0)
; template <class Epi, class Ptrs>
; __device__ __forceinline__ void gemm_phase(LAS unsigned char* lds, const int K, const StaticOrder& S, const Ptrs& P, const Epi& E) {
;     ...
;             PG8_WAIT_V(6); PG8_BAR; PG8_MMA(1, 1, At, B1); PG8_BAR;
;             PG8_LDB(B0, 1, 0); PG8_SCHED; PG8_LDA(At, 1, 0); PG8_STAGE(PG8_SA(0, 1), a2 + hstep, voffA);
;             PG8_WAIT_L(8); PG8_BAR; PG8_WAIT_L(0); PG8_MMA(0, 0, At, B0); PG8_BAR; PG8_SCHED;
;             PG8_LDB(B1, 1, 1); PG8_STAGE(PG8_SB(1, 0), b3, voffB);
;             PG8_BAR; PG8_WAIT_L(0); PG8_MMA(0, 1, At, B1); PG8_BAR;
;             PG8_LDA(At, 1, 1); PG8_STAGE(PG8_SA(1, 0), a3, voffA);
;             PG8_BAR; PG8_WAIT_L(0); PG8_MMA(1, 0, At, B0); PG8_BAR; PG8_SCHED;
	s_add_u32 s70, s42, 0x40000
	s_addc_u32 s71, s43, 0
	s_add_i32 s69, s67, s51
	v_lshl_add_u64 v[128:129], s[70:71], 0, v[178:179]
	s_mov_b32 m0, s69
	s_nop 0
	global_load_lds_dwordx4 v[128:129], off
	v_lshl_add_u64 v[128:129], s[70:71], 0, v[182:183]
	s_add_i32 m0, s69, 0x2000
	s_nop 0
	global_load_lds_dwordx4 v[128:129], off
	s_waitcnt vmcnt(6)
	s_barrier
	s_setprio 1
	v_mfma_f32_16x16x32_bf16 v[52:55], v[192:195], v[144:147], v[52:55]
	v_mfma_f32_16x16x32_bf16 v[48:51], v[200:203], v[144:147], v[48:51]
	v_mfma_f32_16x16x32_bf16 v[32:35], v[200:203], v[152:155], v[32:35]
	v_mfma_f32_16x16x32_bf16 v[36:39], v[192:195], v[152:155], v[36:39]
	v_mfma_f32_16x16x32_bf16 v[20:23], v[192:195], v[160:163], v[20:23]
	v_mfma_f32_16x16x32_bf16 v[16:19], v[200:203], v[160:163], v[16:19]
	v_mfma_f32_16x16x32_bf16 v[0:3], v[200:203], v[168:171], v[0:3]
	v_mfma_f32_16x16x32_bf16 v[4:7], v[192:195], v[168:171], v[4:7]
	v_mfma_f32_16x16x32_bf16 v[52:55], v[196:199], v[148:151], v[52:55]
	v_mfma_f32_16x16x32_bf16 v[48:51], v[212:215], v[148:151], v[48:51]
	v_mfma_f32_16x16x32_bf16 v[32:35], v[212:215], v[156:159], v[32:35]
	v_mfma_f32_16x16x32_bf16 v[36:39], v[196:199], v[156:159], v[36:39]
	v_mfma_f32_16x16x32_bf16 v[20:23], v[196:199], v[164:167], v[20:23]
	v_mfma_f32_16x16x32_bf16 v[16:19], v[212:215], v[164:167], v[16:19]
	v_mfma_f32_16x16x32_bf16 v[0:3], v[212:215], v[172:175], v[0:3]
	v_mfma_f32_16x16x32_bf16 v[4:7], v[196:199], v[172:175], v[4:7]
	s_setprio 0
	s_add_i32 s69, 0, 0x18000
	v_add_u32_e32 v140, s69, v205
	s_barrier
	ds_read_b128 v[128:131], v140
	ds_read_b128 v[132:135], v140 offset:1024
	ds_read_b128 v[136:139], v140 offset:2048
	ds_read_b128 v[140:143], v140 offset:3072
	s_add_u32 s44, s44, 0x40000
	s_addc_u32 s45, s45, 0
	s_mov_b32 m0, s56
	v_lshl_add_u64 v[192:193], s[44:45], 0, v[176:177]
	ds_read_b128 v[144:147], v209 offset:32768
	ds_read_b128 v[148:151], v209 offset:33792
	ds_read_b128 v[152:155], v209 offset:34816
	ds_read_b128 v[156:159], v209 offset:35840
	ds_read_b128 v[160:163], v209 offset:36864
	ds_read_b128 v[164:167], v209 offset:37888
	ds_read_b128 v[168:171], v209 offset:38912
	ds_read_b128 v[172:175], v209 offset:39936
	global_load_lds_dwordx4 v[192:193], off
	v_lshl_add_u64 v[192:193], s[44:45], 0, v[180:181]
	s_mov_b32 m0, s57
	s_nop 0
	global_load_lds_dwordx4 v[192:193], off
	s_waitcnt lgkmcnt(8)
	s_barrier
	s_waitcnt lgkmcnt(0)
	s_setprio 1
	s_waitcnt lgkmcnt(0)
	v_mfma_f32_16x16x32_bf16 v[124:127], v[128:131], v[144:147], v[124:127]
	v_mfma_f32_16x16x32_bf16 v[120:123], v[136:139], v[144:147], v[120:123]
	v_mfma_f32_16x16x32_bf16 v[104:107], v[136:139], v[152:155], v[104:107]
	v_mfma_f32_16x16x32_bf16 v[108:111], v[128:131], v[152:155], v[108:111]
	v_mfma_f32_16x16x32_bf16 v[92:95], v[128:131], v[160:163], v[92:95]
	v_mfma_f32_16x16x32_bf16 v[88:91], v[136:139], v[160:163], v[88:91]
	v_mfma_f32_16x16x32_bf16 v[72:75], v[136:139], v[168:171], v[72:75]
	v_mfma_f32_16x16x32_bf16 v[76:79], v[128:131], v[168:171], v[76:79]
	v_mfma_f32_16x16x32_bf16 v[124:127], v[132:135], v[148:151], v[124:127]
	v_mfma_f32_16x16x32_bf16 v[120:123], v[140:143], v[148:151], v[120:123]
	v_mfma_f32_16x16x32_bf16 v[104:107], v[140:143], v[156:159], v[104:107]
	v_mfma_f32_16x16x32_bf16 v[108:111], v[132:135], v[156:159], v[108:111]
	v_mfma_f32_16x16x32_bf16 v[92:95], v[132:135], v[164:167], v[92:95]
	v_mfma_f32_16x16x32_bf16 v[88:91], v[140:143], v[164:167], v[88:91]
	v_mfma_f32_16x16x32_bf16 v[72:75], v[140:143], v[172:175], v[72:75]
	v_mfma_f32_16x16x32_bf16 v[76:79], v[132:135], v[172:175], v[76:79]
	s_setprio 0
	s_barrier
	s_add_i32 s44, 0, 0x1c000
	s_add_i32 s45, s69, s51
	v_add_u32_e32 v211, s44, v205
	v_lshl_add_u64 v[216:217], v[216:217], 0, s[18:19]
	s_mov_b32 m0, s45
	ds_read_b128 v[192:195], v211
	ds_read_b128 v[196:199], v211 offset:1024
	ds_read_b128 v[200:203], v211 offset:2048
	ds_read_b128 v[212:215], v211 offset:3072
	global_load_lds_dwordx4 v[216:217], off
	v_lshl_add_u64 v[216:217], v[218:219], 0, s[18:19]
	s_add_i32 m0, s45, 0x2000
	s_nop 0
	global_load_lds_dwordx4 v[216:217], off
	s_barrier
	s_waitcnt lgkmcnt(0)
	s_setprio 1
	s_waitcnt lgkmcnt(0)
	v_mfma_f32_16x16x32_bf16 v[116:119], v[192:195], v[144:147], v[116:119]
	v_mfma_f32_16x16x32_bf16 v[112:115], v[200:203], v[144:147], v[112:115]
	v_mfma_f32_16x16x32_bf16 v[96:99], v[200:203], v[152:155], v[96:99]
	v_mfma_f32_16x16x32_bf16 v[100:103], v[192:195], v[152:155], v[100:103]
	v_mfma_f32_16x16x32_bf16 v[84:87], v[192:195], v[160:163], v[84:87]
	v_mfma_f32_16x16x32_bf16 v[80:83], v[200:203], v[160:163], v[80:83]
	v_mfma_f32_16x16x32_bf16 v[64:67], v[200:203], v[168:171], v[64:67]
	v_mfma_f32_16x16x32_bf16 v[68:71], v[192:195], v[168:171], v[68:71]
	v_mfma_f32_16x16x32_bf16 v[116:119], v[196:199], v[148:151], v[116:119]
	v_mfma_f32_16x16x32_bf16 v[112:115], v[212:215], v[148:151], v[112:115]
	v_mfma_f32_16x16x32_bf16 v[96:99], v[212:215], v[156:159], v[96:99]
	v_mfma_f32_16x16x32_bf16 v[100:103], v[196:199], v[156:159], v[100:103]
	v_mfma_f32_16x16x32_bf16 v[84:87], v[196:199], v[164:167], v[84:87]
	v_mfma_f32_16x16x32_bf16 v[80:83], v[212:215], v[164:167], v[80:83]
	v_mfma_f32_16x16x32_bf16 v[64:67], v[212:215], v[172:175], v[64:67]
	v_mfma_f32_16x16x32_bf16 v[68:71], v[196:199], v[172:175], v[68:71]
	s_setprio 0
	s_mov_b32 m0, s63
	v_lshl_add_u64 v[216:217], v[220:221], 0, s[18:19]
	s_barrier
	ds_read_b128 v[144:147], v209 offset:49152
	ds_read_b128 v[148:151], v209 offset:50176
	ds_read_b128 v[152:155], v209 offset:51200
	ds_read_b128 v[156:159], v209 offset:52224
	ds_read_b128 v[160:163], v209 offset:53248
	ds_read_b128 v[164:167], v209 offset:54272
	ds_read_b128 v[168:171], v209 offset:55296
	ds_read_b128 v[172:175], v209 offset:56320
	global_load_lds_dwordx4 v[216:217], off
	v_lshl_add_u64 v[216:217], v[222:223], 0, s[18:19]
	s_mov_b32 m0, s64
	s_nop 0
	global_load_lds_dwordx4 v[216:217], off
	s_barrier
; __device__ __forceinline__ unsigned cvt_pk_bf16(float lo, float hi) { unsigned r; asm volatile("v_cvt_pk_bf16_f32 %0, %1, %2" : "=v"(r) : "v"(lo), "v"(hi)); return r; }
; #define PG8_WAIT_V(n) asm volatile("s_waitcnt vmcnt(" #n ")" ::: "memory")
; #define PG8_WAIT_L(n) asm volatile("s_waitcnt lgkmcnt(" #n ")" ::: "memory")
; template <class Epi, class Ptrs>
; __device__ __forceinline__ void gemm_phase(LAS unsigned char* lds, const int K, const StaticOrder& S, const Ptrs& P, const Epi& E) {
;     ...
;             PG8_BAR; PG8_WAIT_L(0); PG8_MMA(0, 1, At, B1); PG8_BAR;
;             PG8_LDA(At, 1, 1); PG8_STAGE(PG8_SA(1, 0), a3, voffA);
;             PG8_BAR; PG8_WAIT_L(0); PG8_MMA(1, 0, At, B0); PG8_BAR; PG8_SCHED;
;             PG8_STAGE(PG8_SB(1, 1), b3 + hstep, voffB);
;             PG8_WAIT_V(6); PG8_BAR; PG8_MMA(1, 1, At, B1); PG8_BAR;
;         }
;     __device__ __forceinline__ void operator()(const f32x4 (&acc)[2][2][4][2], const Unit& u, int ui, int wr, int wc, int fr, int fq) const {
;         const int row0 = u.pm * 256 + wr * 64 + fr, col0 = u.pn * 256 + wc * 32 + 8 * fq;
;         const float* xb0 = (u.pm * 256 < MP) ? xp : xs - (size_t)MP * DM;
; #pragma unroll
;         for (int ai = 0; ai < 2; ++ai) {
;             f32x4 xv[4][2][2];
; #pragma unroll
;             for (int m = 0; m < 4; ++m)
; #pragma unroll
;                 for (int bj = 0; bj < 2; ++bj) { const float* p = xb0 + (size_t)(row0 + ai * 128 + m * 16) * DM + col0 + bj * 128; xv[m][bj][0] = *(const f32x4*)p; xv[m][bj][1] = *(const f32x4*)(p + 4); }
; #pragma unroll
;             for (int m = 0; m < 4; ++m) { const int row = row0 + ai * 128 + m * 16; const size_t off = (size_t)row * DM + col0; float ss = 0.f;
; #pragma unroll
;                 for (int bj = 0; bj < 2; ++bj) {
;                     const f32x4 v0 = acc[ai][bj][m][0] + xv[m][bj][0], v1 = acc[ai][bj][m][1] + xv[m][bj][1];
;                     u32x4 w; w.x = cvt_pk_bf16(v0[0], v0[1]); w.y = cvt_pk_bf16(v0[2], v0[3]); w.z = cvt_pk_bf16(v1[0], v1[1]); w.w = cvt_pk_bf16(v1[2], v1[3]);
;                     *(u32x4*)(xb + off + bj * 128) = w;
;                     ss += (v0[0] * v0[0] + v0[1] * v0[1]) + (v0[2] * v0[2] + v0[3] * v0[3]) + (v1[0] * v1[0] + v1[1] * v1[1]) + (v1[2] * v1[2] + v1[3] * v1[3]); }
;                 ss = x32_sum(x16_sum(ss));
;                 if (fq == 0) part[(size_t)row * 16 + u.pn * 4 + wc] = ss; }
	s_waitcnt lgkmcnt(0)
	s_setprio 1
	s_waitcnt lgkmcnt(0)
	v_mfma_f32_16x16x32_bf16 v[60:63], v[128:131], v[144:147], v[60:63]
	v_mfma_f32_16x16x32_bf16 v[56:59], v[136:139], v[144:147], v[56:59]
	v_mfma_f32_16x16x32_bf16 v[40:43], v[136:139], v[152:155], v[40:43]
	v_mfma_f32_16x16x32_bf16 v[44:47], v[128:131], v[152:155], v[44:47]
	v_mfma_f32_16x16x32_bf16 v[28:31], v[128:131], v[160:163], v[28:31]
	v_mfma_f32_16x16x32_bf16 v[24:27], v[136:139], v[160:163], v[24:27]
	v_mfma_f32_16x16x32_bf16 v[8:11], v[136:139], v[168:171], v[8:11]
	v_mfma_f32_16x16x32_bf16 v[12:15], v[128:131], v[168:171], v[12:15]
	v_mfma_f32_16x16x32_bf16 v[60:63], v[132:135], v[148:151], v[60:63]
	v_mfma_f32_16x16x32_bf16 v[56:59], v[140:143], v[148:151], v[56:59]
	v_mfma_f32_16x16x32_bf16 v[40:43], v[140:143], v[156:159], v[40:43]
	v_mfma_f32_16x16x32_bf16 v[44:47], v[132:135], v[156:159], v[44:47]
	v_mfma_f32_16x16x32_bf16 v[28:31], v[132:135], v[164:167], v[28:31]
	v_mfma_f32_16x16x32_bf16 v[24:27], v[140:143], v[164:167], v[24:27]
	v_mfma_f32_16x16x32_bf16 v[8:11], v[140:143], v[172:175], v[8:11]
	v_mfma_f32_16x16x32_bf16 v[12:15], v[132:135], v[172:175], v[12:15]
	s_setprio 0
	s_barrier
	s_add_u32 s42, s42, 0x40080
	s_addc_u32 s43, s43, 0
	s_add_i32 s44, s44, s51
	v_lshl_add_u64 v[128:129], s[42:43], 0, v[178:179]
	s_mov_b32 m0, s44
	s_nop 0
	global_load_lds_dwordx4 v[128:129], off
	v_lshl_add_u64 v[128:129], s[42:43], 0, v[182:183]
	s_add_i32 m0, s44, 0x2000
	s_nop 0
	global_load_lds_dwordx4 v[128:129], off
	s_waitcnt vmcnt(6)
	s_barrier
	s_setprio 1
	v_mfma_f32_16x16x32_bf16 v[52:55], v[192:195], v[144:147], v[52:55]
	v_mfma_f32_16x16x32_bf16 v[48:51], v[200:203], v[144:147], v[48:51]
	v_mfma_f32_16x16x32_bf16 v[32:35], v[200:203], v[152:155], v[32:35]
	v_mfma_f32_16x16x32_bf16 v[36:39], v[192:195], v[152:155], v[36:39]
	v_mfma_f32_16x16x32_bf16 v[20:23], v[192:195], v[160:163], v[20:23]
	v_mfma_f32_16x16x32_bf16 v[16:19], v[200:203], v[160:163], v[16:19]
	v_mfma_f32_16x16x32_bf16 v[0:3], v[200:203], v[168:171], v[0:3]
	v_mfma_f32_16x16x32_bf16 v[4:7], v[192:195], v[168:171], v[4:7]
	v_mfma_f32_16x16x32_bf16 v[52:55], v[196:199], v[148:151], v[52:55]
	v_mfma_f32_16x16x32_bf16 v[48:51], v[212:215], v[148:151], v[48:51]
	v_mfma_f32_16x16x32_bf16 v[32:35], v[212:215], v[156:159], v[32:35]
	v_mfma_f32_16x16x32_bf16 v[36:39], v[196:199], v[156:159], v[36:39]
	v_mfma_f32_16x16x32_bf16 v[20:23], v[196:199], v[164:167], v[20:23]
	v_mfma_f32_16x16x32_bf16 v[16:19], v[212:215], v[164:167], v[16:19]
	v_mfma_f32_16x16x32_bf16 v[0:3], v[212:215], v[172:175], v[0:3]
	v_mfma_f32_16x16x32_bf16 v[4:7], v[196:199], v[172:175], v[4:7]
	s_setprio 0
	s_add_i32 s41, s41, 2
	s_add_u32 s38, s38, 0x100
	s_addc_u32 s39, s39, 0
	s_add_u32 s21, s21, 0x100
	s_addc_u32 s23, s23, 0
	s_cmp_gt_u32 s41, 13
	s_barrier
	s_cbranch_scc0 .LBB0_353
	s_cmpk_lt_i32 s40, 0x80
	v_lshl_add_u32 v194, s40, 8, v204
	v_lshl_or_b32 v192, s12, 8, v206
	s_cselect_b32 s21, s37, s61
	s_cselect_b32 s23, s36, s60
	v_mov_b32_e32 v128, s23
	v_mov_b32_e32 v129, s21
	v_ashrrev_i32_e32 v193, 31, v192
	v_ashrrev_i32_e32 v195, 31, v194
	v_lshl_add_u64 v[196:197], v[192:193], 2, v[128:129]
	v_lshlrev_b64 v[128:129], 12, v[194:195]
	v_or_b32_e32 v202, 16, v194
	v_or_b32_e32 v200, 32, v194
	v_or_b32_e32 v198, 48, v194
	v_lshl_add_u64 v[128:129], v[196:197], 0, v[128:129]
	v_ashrrev_i32_e32 v203, 31, v202
	v_ashrrev_i32_e32 v201, 31, v200
	v_ashrrev_i32_e32 v199, 31, v198
	global_load_dwordx4 v[212:215], v[128:129], off
	global_load_dwordx4 v[216:219], v[128:129], off offset:16
	global_load_dwordx4 v[220:223], v[128:129], off offset:512
	global_load_dwordx4 v[224:227], v[128:129], off offset:528
	v_lshlrev_b64 v[128:129], 12, v[202:203]
	v_lshlrev_b64 v[130:131], 12, v[200:201]
	v_lshlrev_b64 v[132:133], 12, v[198:199]
	v_lshl_add_u64 v[128:129], v[196:197], 0, v[128:129]
	v_lshl_add_u64 v[130:131], v[196:197], 0, v[130:131]
	v_lshl_add_u64 v[132:133], v[196:197], 0, v[132:133]
	global_load_dwordx4 v[168:171], v[128:129], off offset:16
	global_load_dwordx4 v[172:175], v[128:129], off
	global_load_dwordx4 v[160:163], v[128:129], off offset:528
	global_load_dwordx4 v[164:167], v[128:129], off offset:512
	global_load_dwordx4 v[152:155], v[130:131], off offset:16
	global_load_dwordx4 v[156:159], v[130:131], off
	global_load_dwordx4 v[144:147], v[130:131], off offset:528
	global_load_dwordx4 v[148:151], v[130:131], off offset:512
	global_load_dwordx4 v[136:139], v[132:133], off offset:16
	global_load_dwordx4 v[140:143], v[132:133], off
	s_nop 0
	global_load_dwordx4 v[128:131], v[132:133], off offset:528
	s_nop 0
	global_load_dwordx4 v[132:135], v[132:133], off offset:512
	v_lshlrev_b64 v[228:229], 11, v[194:195]
	v_lshl_add_u64 v[228:229], s[14:15], 0, v[228:229]
	v_lshl_add_u64 v[228:229], v[192:193], 1, v[228:229]
	s_lshl_b32 s38, s12, 2
	s_ashr_i32 s39, s38, 31
	s_waitcnt vmcnt(0)
	v_pk_add_f32 v[126:127], v[126:127], v[214:215]
	v_pk_add_f32 v[124:125], v[124:125], v[212:213]
	v_pk_add_f32 v[118:119], v[118:119], v[222:223]
	v_pk_add_f32 v[116:117], v[116:117], v[220:221]
	v_pk_add_f32 v[120:121], v[120:121], v[216:217]
	v_pk_add_f32 v[214:215], v[112:113], v[224:225]
	v_cvt_pk_bf16_f32 v112, v124, v125
	v_cvt_pk_bf16_f32 v113, v126, v127
	v_mul_f32_e32 v125, v125, v125
	v_mul_f32_e32 v127, v127, v127
	v_mul_f32_e32 v211, v117, v117
	v_mul_f32_e32 v216, v119, v119
	v_pk_add_f32 v[122:123], v[122:123], v[218:219]
	v_pk_add_f32 v[212:213], v[114:115], v[226:227]
	v_cvt_pk_bf16_f32 v114, v120, v121
	v_cvt_pk_bf16_f32 v115, v122, v123
	v_mul_f32_e32 v121, v121, v121
	v_mul_f32_e32 v217, v215, v215
	global_store_dwordx4 v[228:229], v[112:115], off
	v_fmac_f32_e32 v125, v124, v124
	v_fmac_f32_e32 v127, v126, v126
	v_cvt_pk_bf16_f32 v112, v116, v117
	v_fmac_f32_e32 v211, v116, v116
	v_fmac_f32_e32 v216, v118, v118
	v_mul_f32_e32 v123, v123, v123
	v_mul_f32_e32 v218, v213, v213
	v_fmac_f32_e32 v121, v120, v120
	v_cvt_pk_bf16_f32 v113, v118, v119
	v_cvt_pk_bf16_f32 v114, v214, v215
	v_cvt_pk_bf16_f32 v115, v212, v213
	v_fmac_f32_e32 v217, v214, v214
	v_add_f32_e32 v116, v125, v127
	global_store_dwordx4 v[228:229], v[112:115], off offset:256
	v_fmac_f32_e32 v123, v122, v122
	v_fmac_f32_e32 v218, v212, v212
	v_add_f32_e32 v112, v211, v216
	v_add_f32_e32 v113, v116, v121
	v_add_f32_e32 v112, v112, v217
	v_add_f32_e32 v113, v123, v113
	v_add_f32_e32 v112, v218, v112
	v_add_f32_e32 v112, v113, v112
	v_mov_b32_e32 v113, v112
	s_nop 1
	v_permlane16_swap_b32_e32 v112, v113
	v_add_f32_e32 v112, v112, v113
	v_mov_b32_e32 v113, v112
	s_nop 1
	v_permlane32_swap_b32_e32 v112, v113
	s_and_saveexec_b64 s[40:41], s[6:7]
	s_cbranch_execz .LBB0_356
	v_lshlrev_b64 v[114:115], 6, v[194:195]
	v_lshl_add_u64 v[114:115], s[16:17], 0, v[114:115]
	v_lshl_add_u64 v[114:115], s[38:39], 2, v[114:115]
	s_lshl_b32 s12, s62, 2
	v_lshl_add_u64 v[114:115], v[114:115], 0, s[12:13]
	v_add_f32_e32 v112, v112, v113
	global_store_dword v[114:115], v112, off

; #define PG8_STAGE(bufoff, gbase, voff) do { _Pragma("unroll") for (int _i = 0; _i < 2; ++_i) \
;         __builtin_amdgcn_global_load_lds((const unsigned*)((const char*)(gbase) + (voff)[_i]), (LAS unsigned*)(lds + (bufoff) + ldsw + _i * 8192), 16, 0, 0); } while (0)
; #define PG8_LDA(dst, b, h) do { _Pragma("unroll") for (int m = 0; m < 4; ++m) _Pragma("unroll") for (int k = 0; k < 2; ++k) dst[m][k] = *(const LAS bf16x8*)(lds + PG8_SA(b, h) + aoff + m * 2048 + k * 1024); } while (0)
; #define PG8_LDB(dst, b, h) do { _Pragma("unroll") for (int n = 0; n < 2; ++n) _Pragma("unroll") for (int k = 0; k < 2; ++k) dst[n][k] = *(const LAS bf16x8*)(lds + PG8_SB(b, h) + boff + n * 2048 + k * 1024); } while (0)
; #define PG8_MMA(ai, bj, At, Bt) do { __builtin_amdgcn_s_setprio(1); _Pragma("unroll") for (int m = 0; m < 4; ++m) _Pragma("unroll") for (int n = 0; n < 2; ++n) _Pragma("unroll") for (int k = 0; k < 2; ++k) \
;         acc[ai][bj][m][n] = __builtin_amdgcn_mfma_f32_16x16x32_bf16(Bt[n][k], At[m][k], acc[ai][bj][m][n], 0, 0, 0); __builtin_amdgcn_s_setprio(0); } while (0)
; #define PG8_WAIT_L(n) asm volatile("s_waitcnt lgkmcnt(" #n ")" ::: "memory")
; #define PG8_BAR __builtin_amdgcn_s_barrier()
; #define PG8_SCHED __builtin_amdgcn_sched_barrier(0)
; template <class Epi, class Ptrs>
; __device__ __forceinline__ void gemm_phase(LAS unsigned char* lds, const int K, const StaticOrder& S, const Ptrs& P, const Epi& E) {
;     ...
;             PG8_LDB(B0, 0, 0); PG8_SCHED; PG8_LDA(At, 0, 0); PG8_STAGE(PG8_SA(1, 1), a1 + hstep, voffA);
;             PG8_WAIT_L(8); PG8_BAR; PG8_WAIT_L(0); PG8_MMA(0, 0, At, B0); PG8_BAR; PG8_SCHED;
;             PG8_LDB(B1, 0, 1); PG8_STAGE(PG8_SB(0, 0), b2, voffB);
;             PG8_BAR; PG8_WAIT_L(0); PG8_MMA(0, 1, At, B1); PG8_BAR;
;             PG8_LDA(At, 0, 1); PG8_STAGE(PG8_SA(0, 0), a2, voffA);
;             PG8_BAR; PG8_WAIT_L(0); PG8_MMA(1, 0, At, B0); PG8_BAR; PG8_SCHED;
.LBB0_433:
	ds_read_b128 v[152:155], v149
	ds_read_b128 v[156:159], v149 offset:1024
	ds_read_b128 v[160:163], v149 offset:2048
	ds_read_b128 v[164:167], v149 offset:3072
	s_add_u32 s42, s40, 0xfffc0080
	s_addc_u32 s43, s41, -1
	s_cmp_eq_u32 s70, 12
	s_cselect_b32 s45, s1, s43
	s_cselect_b32 s44, s0, s42
	s_cselect_b32 s43, s37, s25
	s_cselect_b32 s42, s36, s23
	v_lshl_add_u64 v[144:145], s[40:41], 0, v[136:137]
	s_add_i32 m0, s39, 0xc000
	ds_read_b128 v[168:171], v150
	ds_read_b128 v[172:175], v150 offset:1024
	ds_read_b128 v[176:179], v150 offset:2048
	ds_read_b128 v[180:183], v150 offset:3072
	ds_read_b128 v[184:187], v150 offset:4096
	ds_read_b128 v[188:191], v150 offset:5120
	ds_read_b128 v[192:195], v150 offset:6144
	ds_read_b128 v[196:199], v150 offset:7168
	global_load_lds_dwordx4 v[144:145], off
	v_lshl_add_u64 v[144:145], s[40:41], 0, v[138:139]
	s_add_i32 m0, s39, 0xe000
	s_nop 0
	global_load_lds_dwordx4 v[144:145], off
	s_waitcnt lgkmcnt(8)
	s_barrier
	s_waitcnt lgkmcnt(0)
	s_setprio 1
	s_waitcnt lgkmcnt(0)
	v_mfma_f32_16x16x32_bf16 v[124:127], v[152:155], v[168:171], v[124:127]
	v_mfma_f32_16x16x32_bf16 v[120:123], v[160:163], v[168:171], v[120:123]
	v_mfma_f32_16x16x32_bf16 v[104:107], v[160:163], v[176:179], v[104:107]
	v_mfma_f32_16x16x32_bf16 v[108:111], v[152:155], v[176:179], v[108:111]
	v_mfma_f32_16x16x32_bf16 v[92:95], v[152:155], v[184:187], v[92:95]
	v_mfma_f32_16x16x32_bf16 v[88:91], v[160:163], v[184:187], v[88:91]
	v_mfma_f32_16x16x32_bf16 v[72:75], v[160:163], v[192:195], v[72:75]
	v_mfma_f32_16x16x32_bf16 v[76:79], v[152:155], v[192:195], v[76:79]
	v_mfma_f32_16x16x32_bf16 v[124:127], v[156:159], v[172:175], v[124:127]
	v_mfma_f32_16x16x32_bf16 v[120:123], v[164:167], v[172:175], v[120:123]
	v_mfma_f32_16x16x32_bf16 v[104:107], v[164:167], v[180:183], v[104:107]
	v_mfma_f32_16x16x32_bf16 v[108:111], v[156:159], v[180:183], v[108:111]
	v_mfma_f32_16x16x32_bf16 v[92:95], v[156:159], v[188:191], v[92:95]
	v_mfma_f32_16x16x32_bf16 v[88:91], v[164:167], v[188:191], v[88:91]
	v_mfma_f32_16x16x32_bf16 v[72:75], v[164:167], v[196:199], v[72:75]
	v_mfma_f32_16x16x32_bf16 v[76:79], v[156:159], v[196:199], v[76:79]
	s_setprio 0
	s_barrier
	s_add_i32 s71, s63, s51
	v_lshl_add_u64 v[144:145], s[42:43], 0, v[130:131]
	s_mov_b32 m0, s71
	ds_read_b128 v[200:203], v151
	ds_read_b128 v[204:207], v151 offset:1024
	ds_read_b128 v[210:213], v151 offset:2048
	ds_read_b128 v[214:217], v151 offset:3072
	global_load_lds_dwordx4 v[144:145], off
	v_lshl_add_u64 v[218:219], s[42:43], 0, v[134:135]
	s_add_i32 m0, s71, 0x2000
	s_nop 0
	global_load_lds_dwordx4 v[218:219], off
	s_barrier
	s_waitcnt lgkmcnt(0)
	s_setprio 1
	s_waitcnt lgkmcnt(0)
	v_mfma_f32_16x16x32_bf16 v[116:119], v[200:203], v[168:171], v[116:119]
	v_mfma_f32_16x16x32_bf16 v[112:115], v[210:213], v[168:171], v[112:115]
	v_mfma_f32_16x16x32_bf16 v[96:99], v[210:213], v[176:179], v[96:99]
	v_mfma_f32_16x16x32_bf16 v[100:103], v[200:203], v[176:179], v[100:103]
	v_mfma_f32_16x16x32_bf16 v[84:87], v[200:203], v[184:187], v[84:87]
	v_mfma_f32_16x16x32_bf16 v[80:83], v[210:213], v[184:187], v[80:83]
	v_mfma_f32_16x16x32_bf16 v[64:67], v[210:213], v[192:195], v[64:67]
	v_mfma_f32_16x16x32_bf16 v[68:71], v[200:203], v[192:195], v[68:71]
	v_mfma_f32_16x16x32_bf16 v[116:119], v[204:207], v[172:175], v[116:119]
	v_mfma_f32_16x16x32_bf16 v[112:115], v[214:217], v[172:175], v[112:115]
	v_mfma_f32_16x16x32_bf16 v[96:99], v[214:217], v[180:183], v[96:99]
	v_mfma_f32_16x16x32_bf16 v[100:103], v[204:207], v[180:183], v[100:103]
	v_mfma_f32_16x16x32_bf16 v[84:87], v[204:207], v[188:191], v[84:87]
	v_mfma_f32_16x16x32_bf16 v[80:83], v[214:217], v[188:191], v[80:83]
	v_mfma_f32_16x16x32_bf16 v[64:67], v[214:217], v[196:199], v[64:67]
	v_mfma_f32_16x16x32_bf16 v[68:71], v[204:207], v[196:199], v[68:71]
	s_setprio 0
	s_mov_b32 m0, s39
	v_lshl_add_u64 v[220:221], s[44:45], 0, v[128:129]
	s_barrier
	ds_read_b128 v[168:171], v150 offset:16384
	ds_read_b128 v[172:175], v150 offset:17408
	ds_read_b128 v[176:179], v150 offset:18432
	ds_read_b128 v[180:183], v150 offset:19456
	ds_read_b128 v[184:187], v150 offset:20480
	ds_read_b128 v[188:191], v150 offset:21504
	ds_read_b128 v[192:195], v150 offset:22528
	ds_read_b128 v[196:199], v150 offset:23552
	global_load_lds_dwordx4 v[220:221], off
	v_lshl_add_u64 v[222:223], s[44:45], 0, v[132:133]
	s_mov_b32 m0, s56
	s_nop 0
	global_load_lds_dwordx4 v[222:223], off
	s_barrier
	s_waitcnt lgkmcnt(0)
	s_setprio 1
	s_waitcnt lgkmcnt(0)
	v_mfma_f32_16x16x32_bf16 v[60:63], v[152:155], v[168:171], v[60:63]
	v_mfma_f32_16x16x32_bf16 v[56:59], v[160:163], v[168:171], v[56:59]
	v_mfma_f32_16x16x32_bf16 v[40:43], v[160:163], v[176:179], v[40:43]
	v_mfma_f32_16x16x32_bf16 v[44:47], v[152:155], v[176:179], v[44:47]
	v_mfma_f32_16x16x32_bf16 v[28:31], v[152:155], v[184:187], v[28:31]
	v_mfma_f32_16x16x32_bf16 v[24:27], v[160:163], v[184:187], v[24:27]
	v_mfma_f32_16x16x32_bf16 v[8:11], v[160:163], v[192:195], v[8:11]
	v_mfma_f32_16x16x32_bf16 v[12:15], v[152:155], v[192:195], v[12:15]
	v_mfma_f32_16x16x32_bf16 v[60:63], v[156:159], v[172:175], v[60:63]
	v_mfma_f32_16x16x32_bf16 v[56:59], v[164:167], v[172:175], v[56:59]
	v_mfma_f32_16x16x32_bf16 v[40:43], v[164:167], v[180:183], v[40:43]
	v_mfma_f32_16x16x32_bf16 v[44:47], v[156:159], v[180:183], v[44:47]
	v_mfma_f32_16x16x32_bf16 v[28:31], v[156:159], v[188:191], v[28:31]
	v_mfma_f32_16x16x32_bf16 v[24:27], v[164:167], v[188:191], v[24:27]
	v_mfma_f32_16x16x32_bf16 v[8:11], v[164:167], v[196:199], v[8:11]
	v_mfma_f32_16x16x32_bf16 v[12:15], v[156:159], v[196:199], v[12:15]
	s_setprio 0
	s_barrier
; #define PG8_STAGE(bufoff, gbase, voff) do { _Pragma("unroll") for (int _i = 0; _i < 2; ++_i) \
;         __builtin_amdgcn_global_load_lds((const unsigned*)((const char*)(gbase) + (voff)[_i]), (LAS unsigned*)(lds + (bufoff) + ldsw + _i * 8192), 16, 0, 0); } while (0)
; #define PG8_LDA(dst, b, h) do { _Pragma("unroll") for (int m = 0; m < 4; ++m) _Pragma("unroll") for (int k = 0; k < 2; ++k) dst[m][k] = *(const LAS bf16x8*)(lds + PG8_SA(b, h) + aoff + m * 2048 + k * 1024); } while (0)
; #define PG8_LDB(dst, b, h) do { _Pragma("unroll") for (int n = 0; n < 2; ++n) _Pragma("unroll") for (int k = 0; k < 2; ++k) dst[n][k] = *(const LAS bf16x8*)(lds + PG8_SB(b, h) + boff + n * 2048 + k * 1024); } while (0)
; #define PG8_MMA(ai, bj, At, Bt) do { __builtin_amdgcn_s_setprio(1); _Pragma("unroll") for (int m = 0; m < 4; ++m) _Pragma("unroll") for (int n = 0; n < 2; ++n) _Pragma("unroll") for (int k = 0; k < 2; ++k) \
;         acc[ai][bj][m][n] = __builtin_amdgcn_mfma_f32_16x16x32_bf16(Bt[n][k], At[m][k], acc[ai][bj][m][n], 0, 0, 0); __builtin_amdgcn_s_setprio(0); } while (0)
; #define PG8_WAIT_V(n) asm volatile("s_waitcnt vmcnt(" #n ")" ::: "memory")
; #define PG8_WAIT_L(n) asm volatile("s_waitcnt lgkmcnt(" #n ")" ::: "memory")
; #define PG8_BAR __builtin_amdgcn_s_barrier()
; #define PG8_SCHED __builtin_amdgcn_sched_barrier(0)
; template <class Epi, class Ptrs>
; __device__ __forceinline__ void gemm_phase(LAS unsigned char* lds, const int K, const StaticOrder& S, const Ptrs& P, const Epi& E) {
;     ...
;             PG8_STAGE(PG8_SB(0, 1), b2 + hstep, voffB);
;             PG8_WAIT_V(6); PG8_BAR; PG8_MMA(1, 1, At, B1); PG8_BAR;
;             PG8_LDB(B0, 1, 0); PG8_SCHED; PG8_LDA(At, 1, 0); PG8_STAGE(PG8_SA(0, 1), a2 + hstep, voffA);
;             PG8_WAIT_L(8); PG8_BAR; PG8_WAIT_L(0); PG8_MMA(0, 0, At, B0); PG8_BAR; PG8_SCHED;
;             PG8_LDB(B1, 1, 1); PG8_STAGE(PG8_SB(1, 0), b3, voffB);
;             PG8_BAR; PG8_WAIT_L(0); PG8_MMA(0, 1, At, B1); PG8_BAR;
;             PG8_LDA(At, 1, 1); PG8_STAGE(PG8_SA(1, 0), a3, voffA);
	s_add_u32 s72, s42, 0x40000
	s_addc_u32 s73, s43, 0
	s_add_i32 s71, s64, s51
	v_lshl_add_u64 v[152:153], s[72:73], 0, v[130:131]
	s_mov_b32 m0, s71
	s_nop 0
	global_load_lds_dwordx4 v[152:153], off
	v_lshl_add_u64 v[152:153], s[72:73], 0, v[134:135]
	s_add_i32 m0, s71, 0x2000
	s_nop 0
	global_load_lds_dwordx4 v[152:153], off
	s_waitcnt vmcnt(6)
	s_barrier
	s_setprio 1
	v_mfma_f32_16x16x32_bf16 v[52:55], v[200:203], v[168:171], v[52:55]
	v_mfma_f32_16x16x32_bf16 v[48:51], v[210:213], v[168:171], v[48:51]
	v_mfma_f32_16x16x32_bf16 v[32:35], v[210:213], v[176:179], v[32:35]
	v_mfma_f32_16x16x32_bf16 v[36:39], v[200:203], v[176:179], v[36:39]
	v_mfma_f32_16x16x32_bf16 v[20:23], v[200:203], v[184:187], v[20:23]
	v_mfma_f32_16x16x32_bf16 v[16:19], v[210:213], v[184:187], v[16:19]
	v_mfma_f32_16x16x32_bf16 v[0:3], v[210:213], v[192:195], v[0:3]
	v_mfma_f32_16x16x32_bf16 v[4:7], v[200:203], v[192:195], v[4:7]
	v_mfma_f32_16x16x32_bf16 v[52:55], v[204:207], v[172:175], v[52:55]
	v_mfma_f32_16x16x32_bf16 v[48:51], v[214:217], v[172:175], v[48:51]
	v_mfma_f32_16x16x32_bf16 v[32:35], v[214:217], v[180:183], v[32:35]
	v_mfma_f32_16x16x32_bf16 v[36:39], v[204:207], v[180:183], v[36:39]
	v_mfma_f32_16x16x32_bf16 v[20:23], v[204:207], v[188:191], v[20:23]
	v_mfma_f32_16x16x32_bf16 v[16:19], v[214:217], v[188:191], v[16:19]
	v_mfma_f32_16x16x32_bf16 v[0:3], v[214:217], v[196:199], v[0:3]
	v_mfma_f32_16x16x32_bf16 v[4:7], v[204:207], v[196:199], v[4:7]
	s_setprio 0
	s_add_i32 s71, 0, 0x18000
	v_add_u32_e32 v164, s71, v147
	s_barrier
	ds_read_b128 v[152:155], v164
	ds_read_b128 v[156:159], v164 offset:1024
	ds_read_b128 v[160:163], v164 offset:2048
	ds_read_b128 v[164:167], v164 offset:3072
	s_add_u32 s44, s44, 0x40000
	s_addc_u32 s45, s45, 0
	s_mov_b32 m0, s57
	v_lshl_add_u64 v[200:201], s[44:45], 0, v[128:129]
	ds_read_b128 v[168:171], v150 offset:32768
	ds_read_b128 v[172:175], v150 offset:33792
	ds_read_b128 v[176:179], v150 offset:34816
	ds_read_b128 v[180:183], v150 offset:35840
	ds_read_b128 v[184:187], v150 offset:36864
	ds_read_b128 v[188:191], v150 offset:37888
	ds_read_b128 v[192:195], v150 offset:38912
	ds_read_b128 v[196:199], v150 offset:39936
	global_load_lds_dwordx4 v[200:201], off
	v_lshl_add_u64 v[200:201], s[44:45], 0, v[132:133]
	s_mov_b32 m0, s58
	s_nop 0
	global_load_lds_dwordx4 v[200:201], off
	s_waitcnt lgkmcnt(8)
	s_barrier
	s_waitcnt lgkmcnt(0)
	s_setprio 1
	s_waitcnt lgkmcnt(0)
	v_mfma_f32_16x16x32_bf16 v[124:127], v[152:155], v[168:171], v[124:127]
	v_mfma_f32_16x16x32_bf16 v[120:123], v[160:163], v[168:171], v[120:123]
	v_mfma_f32_16x16x32_bf16 v[104:107], v[160:163], v[176:179], v[104:107]
	v_mfma_f32_16x16x32_bf16 v[108:111], v[152:155], v[176:179], v[108:111]
	v_mfma_f32_16x16x32_bf16 v[92:95], v[152:155], v[184:187], v[92:95]
	v_mfma_f32_16x16x32_bf16 v[88:91], v[160:163], v[184:187], v[88:91]
	v_mfma_f32_16x16x32_bf16 v[72:75], v[160:163], v[192:195], v[72:75]
	v_mfma_f32_16x16x32_bf16 v[76:79], v[152:155], v[192:195], v[76:79]
	v_mfma_f32_16x16x32_bf16 v[124:127], v[156:159], v[172:175], v[124:127]
	v_mfma_f32_16x16x32_bf16 v[120:123], v[164:167], v[172:175], v[120:123]
	v_mfma_f32_16x16x32_bf16 v[104:107], v[164:167], v[180:183], v[104:107]
	v_mfma_f32_16x16x32_bf16 v[108:111], v[156:159], v[180:183], v[108:111]
	v_mfma_f32_16x16x32_bf16 v[92:95], v[156:159], v[188:191], v[92:95]
	v_mfma_f32_16x16x32_bf16 v[88:91], v[164:167], v[188:191], v[88:91]
	v_mfma_f32_16x16x32_bf16 v[72:75], v[164:167], v[196:199], v[72:75]
	v_mfma_f32_16x16x32_bf16 v[76:79], v[156:159], v[196:199], v[76:79]
	s_setprio 0
	s_barrier
	s_add_i32 s44, 0, 0x1c000
	s_add_i32 s45, s71, s51
	v_add_u32_e32 v209, s44, v147
	v_lshl_add_u64 v[144:145], v[144:145], 0, s[12:13]
	s_mov_b32 m0, s45
	ds_read_b128 v[200:203], v209
	ds_read_b128 v[204:207], v209 offset:1024
	ds_read_b128 v[210:213], v209 offset:2048
	ds_read_b128 v[214:217], v209 offset:3072
	global_load_lds_dwordx4 v[144:145], off
	v_lshl_add_u64 v[144:145], v[218:219], 0, s[12:13]
	s_add_i32 m0, s45, 0x2000
	s_nop 0
	global_load_lds_dwordx4 v[144:145], off
	s_barrier
	s_waitcnt lgkmcnt(0)
	s_setprio 1
	s_waitcnt lgkmcnt(0)
	v_mfma_f32_16x16x32_bf16 v[116:119], v[200:203], v[168:171], v[116:119]
	v_mfma_f32_16x16x32_bf16 v[112:115], v[210:213], v[168:171], v[112:115]
	v_mfma_f32_16x16x32_bf16 v[96:99], v[210:213], v[176:179], v[96:99]
	v_mfma_f32_16x16x32_bf16 v[100:103], v[200:203], v[176:179], v[100:103]
	v_mfma_f32_16x16x32_bf16 v[84:87], v[200:203], v[184:187], v[84:87]
	v_mfma_f32_16x16x32_bf16 v[80:83], v[210:213], v[184:187], v[80:83]
	v_mfma_f32_16x16x32_bf16 v[64:67], v[210:213], v[192:195], v[64:67]
	v_mfma_f32_16x16x32_bf16 v[68:71], v[200:203], v[192:195], v[68:71]
	v_mfma_f32_16x16x32_bf16 v[116:119], v[204:207], v[172:175], v[116:119]
	v_mfma_f32_16x16x32_bf16 v[112:115], v[214:217], v[172:175], v[112:115]
	v_mfma_f32_16x16x32_bf16 v[96:99], v[214:217], v[180:183], v[96:99]
	v_mfma_f32_16x16x32_bf16 v[100:103], v[204:207], v[180:183], v[100:103]
	v_mfma_f32_16x16x32_bf16 v[84:87], v[204:207], v[188:191], v[84:87]
	v_mfma_f32_16x16x32_bf16 v[80:83], v[214:217], v[188:191], v[80:83]
	v_mfma_f32_16x16x32_bf16 v[64:67], v[214:217], v[196:199], v[64:67]
	v_mfma_f32_16x16x32_bf16 v[68:71], v[204:207], v[196:199], v[68:71]
	s_setprio 0
	s_mov_b32 m0, s61
	v_lshl_add_u64 v[144:145], v[220:221], 0, s[12:13]
	s_barrier
	ds_read_b128 v[168:171], v150 offset:49152
	ds_read_b128 v[172:175], v150 offset:50176
	ds_read_b128 v[176:179], v150 offset:51200
	ds_read_b128 v[180:183], v150 offset:52224
	ds_read_b128 v[184:187], v150 offset:53248
	ds_read_b128 v[188:191], v150 offset:54272
	ds_read_b128 v[192:195], v150 offset:55296
	ds_read_b128 v[196:199], v150 offset:56320
	global_load_lds_dwordx4 v[144:145], off
	v_lshl_add_u64 v[144:145], v[222:223], 0, s[12:13]
	s_mov_b32 m0, s62
	s_nop 0
	global_load_lds_dwordx4 v[144:145], off
	s_barrier
; __device__ __forceinline__ unsigned cvt_pk_bf16(float lo, float hi) { unsigned r; asm volatile("v_cvt_pk_bf16_f32 %0, %1, %2" : "=v"(r) : "v"(lo), "v"(hi)); return r; }
; #define PG8_STAGE(bufoff, gbase, voff) do { _Pragma("unroll") for (int _i = 0; _i < 2; ++_i) \
;         __builtin_amdgcn_global_load_lds((const unsigned*)((const char*)(gbase) + (voff)[_i]), (LAS unsigned*)(lds + (bufoff) + ldsw + _i * 8192), 16, 0, 0); } while (0)
; #define PG8_MMA(ai, bj, At, Bt) do { __builtin_amdgcn_s_setprio(1); _Pragma("unroll") for (int m = 0; m < 4; ++m) _Pragma("unroll") for (int n = 0; n < 2; ++n) _Pragma("unroll") for (int k = 0; k < 2; ++k) \
;         acc[ai][bj][m][n] = __builtin_amdgcn_mfma_f32_16x16x32_bf16(Bt[n][k], At[m][k], acc[ai][bj][m][n], 0, 0, 0); __builtin_amdgcn_s_setprio(0); } while (0)
; #define PG8_WAIT_V(n) asm volatile("s_waitcnt vmcnt(" #n ")" ::: "memory")
; #define PG8_WAIT_L(n) asm volatile("s_waitcnt lgkmcnt(" #n ")" ::: "memory")
; #define PG8_BAR __builtin_amdgcn_s_barrier()
; #define PG8_SCHED __builtin_amdgcn_sched_barrier(0)
; template <class Epi, class Ptrs>
; __device__ __forceinline__ void gemm_phase(LAS unsigned char* lds, const int K, const StaticOrder& S, const Ptrs& P, const Epi& E) {
;     ...
;             PG8_BAR; PG8_WAIT_L(0); PG8_MMA(1, 0, At, B0); PG8_BAR; PG8_SCHED;
;             PG8_STAGE(PG8_SB(1, 1), b3 + hstep, voffB);
;             PG8_WAIT_V(6); PG8_BAR; PG8_MMA(1, 1, At, B1); PG8_BAR;
;     __device__ __forceinline__ void operator()(const f32x4 (&acc)[2][2][4][2], const Unit& u, int ui, int wr, int wc, int fr, int fq) const {
;     ...
;             for (int m = 0; m < 4; ++m) { bf16_t* rowp = hid + (size_t)(row0 + ai * 128 + m * 16) * DFF + col0;
; #pragma unroll
;                 for (int bj = 0; bj < 2; ++bj) { f32x4 v0 = acc[ai][bj][m][0], v1 = acc[ai][bj][m][1];
; #pragma unroll
;                     for (int j = 0; j < 4; ++j) { const float a = fmaxf(v0[j], 0.f), b = fmaxf(v1[j], 0.f); v0[j] = a * a; v1[j] = b * b; }
;                     u32x4 w; w.x = cvt_pk_bf16(v0[0], v0[1]); w.y = cvt_pk_bf16(v0[2], v0[3]); w.z = cvt_pk_bf16(v1[0], v1[1]); w.w = cvt_pk_bf16(v1[2], v1[3]);
;                     *(u32x4*)(rowp + bj * 128) = w; } }
	s_waitcnt lgkmcnt(0)
	s_setprio 1
	s_waitcnt lgkmcnt(0)
	v_mfma_f32_16x16x32_bf16 v[60:63], v[152:155], v[168:171], v[60:63]
	v_mfma_f32_16x16x32_bf16 v[56:59], v[160:163], v[168:171], v[56:59]
	v_mfma_f32_16x16x32_bf16 v[40:43], v[160:163], v[176:179], v[40:43]
	v_mfma_f32_16x16x32_bf16 v[44:47], v[152:155], v[176:179], v[44:47]
	v_mfma_f32_16x16x32_bf16 v[28:31], v[152:155], v[184:187], v[28:31]
	v_mfma_f32_16x16x32_bf16 v[24:27], v[160:163], v[184:187], v[24:27]
	v_mfma_f32_16x16x32_bf16 v[8:11], v[160:163], v[192:195], v[8:11]
	v_mfma_f32_16x16x32_bf16 v[12:15], v[152:155], v[192:195], v[12:15]
	v_mfma_f32_16x16x32_bf16 v[60:63], v[156:159], v[172:175], v[60:63]
	v_mfma_f32_16x16x32_bf16 v[56:59], v[164:167], v[172:175], v[56:59]
	v_mfma_f32_16x16x32_bf16 v[40:43], v[164:167], v[180:183], v[40:43]
	v_mfma_f32_16x16x32_bf16 v[44:47], v[156:159], v[180:183], v[44:47]
	v_mfma_f32_16x16x32_bf16 v[28:31], v[156:159], v[188:191], v[28:31]
	v_mfma_f32_16x16x32_bf16 v[24:27], v[164:167], v[188:191], v[24:27]
	v_mfma_f32_16x16x32_bf16 v[8:11], v[164:167], v[196:199], v[8:11]
	v_mfma_f32_16x16x32_bf16 v[12:15], v[156:159], v[196:199], v[12:15]
	s_setprio 0
	s_barrier
	s_add_u32 s42, s42, 0x40080
	s_addc_u32 s43, s43, 0
	s_add_i32 s44, s44, s51
	v_lshl_add_u64 v[144:145], s[42:43], 0, v[130:131]
	s_mov_b32 m0, s44
	s_nop 0
	global_load_lds_dwordx4 v[144:145], off
	v_lshl_add_u64 v[144:145], s[42:43], 0, v[134:135]
	s_add_i32 m0, s44, 0x2000
	s_nop 0
	global_load_lds_dwordx4 v[144:145], off
	s_waitcnt vmcnt(6)
	s_barrier
	s_setprio 1
	v_mfma_f32_16x16x32_bf16 v[52:55], v[200:203], v[168:171], v[52:55]
	v_mfma_f32_16x16x32_bf16 v[48:51], v[210:213], v[168:171], v[48:51]
	v_mfma_f32_16x16x32_bf16 v[32:35], v[210:213], v[176:179], v[32:35]
	v_mfma_f32_16x16x32_bf16 v[36:39], v[200:203], v[176:179], v[36:39]
	v_mfma_f32_16x16x32_bf16 v[20:23], v[200:203], v[184:187], v[20:23]
	v_mfma_f32_16x16x32_bf16 v[16:19], v[210:213], v[184:187], v[16:19]
	v_mfma_f32_16x16x32_bf16 v[0:3], v[210:213], v[192:195], v[0:3]
	v_mfma_f32_16x16x32_bf16 v[4:7], v[200:203], v[192:195], v[4:7]
	v_mfma_f32_16x16x32_bf16 v[52:55], v[204:207], v[172:175], v[52:55]
	v_mfma_f32_16x16x32_bf16 v[48:51], v[214:217], v[172:175], v[48:51]
	v_mfma_f32_16x16x32_bf16 v[32:35], v[214:217], v[180:183], v[32:35]
	v_mfma_f32_16x16x32_bf16 v[36:39], v[204:207], v[180:183], v[36:39]
	v_mfma_f32_16x16x32_bf16 v[20:23], v[204:207], v[188:191], v[20:23]
	v_mfma_f32_16x16x32_bf16 v[16:19], v[214:217], v[188:191], v[16:19]
	v_mfma_f32_16x16x32_bf16 v[0:3], v[214:217], v[196:199], v[0:3]
	v_mfma_f32_16x16x32_bf16 v[4:7], v[204:207], v[196:199], v[4:7]
	s_setprio 0
	s_add_i32 s70, s70, 2
	s_add_u32 s40, s40, 0x100
	s_addc_u32 s41, s41, 0
	s_add_u32 s23, s23, 0x100
	s_addc_u32 s25, s25, 0
	s_cmp_gt_u32 s70, 13
	s_barrier
	s_cbranch_scc0 .LBB0_433
	v_lshl_add_u32 v152, s38, 8, v146
	v_max_f32_e32 v120, v120, v120
	v_ashrrev_i32_e32 v153, 31, v152
	v_max_f32_e32 v120, 0, v120
	v_max_f32_e32 v121, v121, v121
	v_max_f32_e32 v122, v122, v122
	v_lshl_or_b32 v144, s69, 8, v148
	v_lshlrev_b64 v[154:155], 13, v[152:153]
	v_mul_f32_e32 v153, v120, v120
	v_max_f32_e32 v120, v125, v125
	v_max_f32_e32 v121, 0, v121
	v_max_f32_e32 v122, 0, v122
	v_ashrrev_i32_e32 v145, 31, v144
	v_max_f32_e32 v124, v124, v124
	v_max_f32_e32 v120, 0, v120
	v_mul_f32_e32 v125, v121, v121
	v_max_f32_e32 v121, v126, v126
	v_mul_f32_e32 v126, v122, v122
	v_max_f32_e32 v122, v127, v127
	v_max_f32_e32 v123, v123, v123
	v_lshl_add_u64 v[154:155], s[10:11], 0, v[154:155]
	v_lshlrev_b64 v[156:157], 1, v[144:145]
	v_max_f32_e32 v124, 0, v124
	v_mul_f32_e32 v120, v120, v120
	v_max_f32_e32 v121, 0, v121
	v_max_f32_e32 v122, 0, v122
	v_max_f32_e32 v123, 0, v123
	v_max_f32_e32 v112, v112, v112
	v_lshl_add_u64 v[144:145], v[154:155], 0, v[156:157]
	v_mul_f32_e32 v124, v124, v124
	v_mul_f32_e32 v121, v121, v121
	v_mul_f32_e32 v122, v122, v122
	v_mul_f32_e32 v123, v123, v123
	v_cvt_pk_bf16_f32 v120, v124, v120
	v_max_f32_e32 v112, 0, v112
	v_max_f32_e32 v113, v113, v113
	v_max_f32_e32 v114, v114, v114
	v_cvt_pk_bf16_f32 v121, v121, v122
	v_cvt_pk_bf16_f32 v122, v153, v125
	v_cvt_pk_bf16_f32 v123, v126, v123
	global_store_dwordx4 v[144:145], v[120:123], off
	v_max_f32_e32 v113, 0, v113
	v_max_f32_e32 v114, 0, v114
	v_mul_f32_e32 v120, v112, v112
	v_max_f32_e32 v112, v117, v117
	v_max_f32_e32 v116, v116, v116
	v_max_f32_e32 v112, 0, v112
	v_mul_f32_e32 v117, v113, v113
	v_max_f32_e32 v113, v118, v118
	v_mul_f32_e32 v118, v114, v114
	v_max_f32_e32 v114, v119, v119
	v_max_f32_e32 v115, v115, v115
	v_max_f32_e32 v116, 0, v116
	v_mul_f32_e32 v112, v112, v112
	v_max_f32_e32 v113, 0, v113
	v_max_f32_e32 v114, 0, v114
	v_max_f32_e32 v115, 0, v115
	v_mul_f32_e32 v116, v116, v116
	v_mul_f32_e32 v113, v113, v113
	v_mul_f32_e32 v114, v114, v114
	v_mul_f32_e32 v115, v115, v115
	v_cvt_pk_bf16_f32 v112, v116, v112
	v_max_f32_e32 v104, v104, v104
	v_cvt_pk_bf16_f32 v113, v113, v114
	v_cvt_pk_bf16_f32 v114, v120, v117
	v_cvt_pk_bf16_f32 v115, v118, v115
	global_store_dwordx4 v[144:145], v[112:115], off offset:256
	v_max_f32_e32 v104, 0, v104
	v_max_f32_e32 v105, v105, v105
	v_or_b32_e32 v112, 16, v152
	v_max_f32_e32 v106, v106, v106
	v_ashrrev_i32_e32 v113, 31, v112
	v_mul_f32_e32 v114, v104, v104
	v_max_f32_e32 v104, v109, v109
	v_max_f32_e32 v105, 0, v105
	v_max_f32_e32 v106, 0, v106
	v_lshlrev_b64 v[112:113], 13, v[112:113]
	v_max_f32_e32 v108, v108, v108
	v_max_f32_e32 v104, 0, v104
	v_mul_f32_e32 v109, v105, v105
	v_max_f32_e32 v105, v110, v110
	v_mul_f32_e32 v110, v106, v106
	v_max_f32_e32 v106, v111, v111
	v_max_f32_e32 v107, v107, v107
; __device__ __forceinline__ unsigned cvt_pk_bf16(float lo, float hi) { unsigned r; asm volatile("v_cvt_pk_bf16_f32 %0, %1, %2" : "=v"(r) : "v"(lo), "v"(hi)); return r; }
;     __device__ __forceinline__ void operator()(const f32x4 (&acc)[2][2][4][2], const Unit& u, int ui, int wr, int wc, int fr, int fq) const {
;     ...
;             for (int m = 0; m < 4; ++m) { bf16_t* rowp = hid + (size_t)(row0 + ai * 128 + m * 16) * DFF + col0;
; #pragma unroll
;                 for (int bj = 0; bj < 2; ++bj) { f32x4 v0 = acc[ai][bj][m][0], v1 = acc[ai][bj][m][1];
; #pragma unroll
;                     for (int j = 0; j < 4; ++j) { const float a = fmaxf(v0[j], 0.f), b = fmaxf(v1[j], 0.f); v0[j] = a * a; v1[j] = b * b; }
;                     u32x4 w; w.x = cvt_pk_bf16(v0[0], v0[1]); w.y = cvt_pk_bf16(v0[2], v0[3]); w.z = cvt_pk_bf16(v1[0], v1[1]); w.w = cvt_pk_bf16(v1[2], v1[3]);
;                     *(u32x4*)(rowp + bj * 128) = w; } }
	v_lshl_add_u64 v[112:113], s[10:11], 0, v[112:113]
	v_max_f32_e32 v108, 0, v108
	v_mul_f32_e32 v104, v104, v104
	v_max_f32_e32 v105, 0, v105
	v_max_f32_e32 v106, 0, v106
	v_max_f32_e32 v107, 0, v107
	v_max_f32_e32 v96, v96, v96
	v_lshl_add_u64 v[112:113], v[112:113], 0, v[156:157]
	v_mul_f32_e32 v108, v108, v108
	v_mul_f32_e32 v105, v105, v105
	v_mul_f32_e32 v106, v106, v106
	v_mul_f32_e32 v107, v107, v107
	v_cvt_pk_bf16_f32 v104, v108, v104
	v_max_f32_e32 v96, 0, v96
	v_max_f32_e32 v97, v97, v97
	v_max_f32_e32 v98, v98, v98
	v_cvt_pk_bf16_f32 v105, v105, v106
	v_cvt_pk_bf16_f32 v106, v114, v109
	v_cvt_pk_bf16_f32 v107, v110, v107
	global_store_dwordx4 v[112:113], v[104:107], off
	v_max_f32_e32 v97, 0, v97
	v_max_f32_e32 v98, 0, v98
	v_mul_f32_e32 v104, v96, v96
	v_max_f32_e32 v96, v101, v101
	v_max_f32_e32 v100, v100, v100
	v_max_f32_e32 v96, 0, v96
	v_mul_f32_e32 v101, v97, v97
	v_max_f32_e32 v97, v102, v102
	v_mul_f32_e32 v102, v98, v98
	v_max_f32_e32 v98, v103, v103
	v_max_f32_e32 v99, v99, v99
	v_max_f32_e32 v100, 0, v100
	v_mul_f32_e32 v96, v96, v96
	v_max_f32_e32 v97, 0, v97
	v_max_f32_e32 v98, 0, v98
	v_max_f32_e32 v99, 0, v99
	v_mul_f32_e32 v100, v100, v100
	v_mul_f32_e32 v97, v97, v97
	v_mul_f32_e32 v98, v98, v98
	v_mul_f32_e32 v99, v99, v99
	v_cvt_pk_bf16_f32 v96, v100, v96
	v_max_f32_e32 v88, v88, v88
	v_cvt_pk_bf16_f32 v97, v97, v98
	v_cvt_pk_bf16_f32 v98, v104, v101
	v_cvt_pk_bf16_f32 v99, v102, v99
	global_store_dwordx4 v[112:113], v[96:99], off offset:256
	v_max_f32_e32 v88, 0, v88
	v_max_f32_e32 v89, v89, v89
	v_or_b32_e32 v96, 32, v152
	v_max_f32_e32 v90, v90, v90
	v_ashrrev_i32_e32 v97, 31, v96
	v_mul_f32_e32 v98, v88, v88
	v_max_f32_e32 v88, v93, v93
	v_max_f32_e32 v89, 0, v89
	v_max_f32_e32 v90, 0, v90
	v_lshlrev_b64 v[96:97], 13, v[96:97]
	v_max_f32_e32 v92, v92, v92
	v_max_f32_e32 v88, 0, v88
	v_mul_f32_e32 v93, v89, v89
	v_max_f32_e32 v89, v94, v94
	v_mul_f32_e32 v94, v90, v90
	v_max_f32_e32 v90, v95, v95
	v_max_f32_e32 v91, v91, v91
	v_lshl_add_u64 v[96:97], s[10:11], 0, v[96:97]
	v_max_f32_e32 v92, 0, v92
	v_mul_f32_e32 v88, v88, v88
	v_max_f32_e32 v89, 0, v89
	v_max_f32_e32 v90, 0, v90
	v_max_f32_e32 v91, 0, v91
	v_max_f32_e32 v80, v80, v80
	v_lshl_add_u64 v[96:97], v[96:97], 0, v[156:157]
	v_mul_f32_e32 v92, v92, v92
	v_mul_f32_e32 v89, v89, v89
	v_mul_f32_e32 v90, v90, v90
	v_mul_f32_e32 v91, v91, v91
	v_cvt_pk_bf16_f32 v88, v92, v88
	v_max_f32_e32 v80, 0, v80
	v_max_f32_e32 v81, v81, v81
	v_max_f32_e32 v82, v82, v82
	v_cvt_pk_bf16_f32 v89, v89, v90
	v_cvt_pk_bf16_f32 v90, v98, v93
	v_cvt_pk_bf16_f32 v91, v94, v91
	global_store_dwordx4 v[96:97], v[88:91], off
	v_max_f32_e32 v81, 0, v81
	v_max_f32_e32 v82, 0, v82
	v_mul_f32_e32 v88, v80, v80
	v_max_f32_e32 v80, v85, v85
	v_max_f32_e32 v84, v84, v84
	v_max_f32_e32 v80, 0, v80
	v_mul_f32_e32 v85, v81, v81
	v_max_f32_e32 v81, v86, v86
	v_mul_f32_e32 v86, v82, v82
	v_max_f32_e32 v82, v87, v87
	v_max_f32_e32 v83, v83, v83
	v_max_f32_e32 v84, 0, v84
	v_mul_f32_e32 v80, v80, v80
	v_max_f32_e32 v81, 0, v81
	v_max_f32_e32 v82, 0, v82
	v_max_f32_e32 v83, 0, v83
	v_mul_f32_e32 v84, v84, v84
	v_mul_f32_e32 v81, v81, v81
	v_mul_f32_e32 v82, v82, v82
	v_mul_f32_e32 v83, v83, v83
	v_cvt_pk_bf16_f32 v80, v84, v80
	v_max_f32_e32 v72, v72, v72
	v_cvt_pk_bf16_f32 v81, v81, v82
	v_cvt_pk_bf16_f32 v82, v88, v85
	v_cvt_pk_bf16_f32 v83, v86, v83
	global_store_dwordx4 v[96:97], v[80:83], off offset:256
	v_max_f32_e32 v72, 0, v72
	v_max_f32_e32 v73, v73, v73
	v_or_b32_e32 v80, 48, v152
	v_max_f32_e32 v74, v74, v74
	v_ashrrev_i32_e32 v81, 31, v80
	v_mul_f32_e32 v82, v72, v72
	v_max_f32_e32 v72, v77, v77
	v_max_f32_e32 v73, 0, v73
	v_max_f32_e32 v74, 0, v74
	v_lshlrev_b64 v[80:81], 13, v[80:81]
	v_max_f32_e32 v76, v76, v76
	v_max_f32_e32 v72, 0, v72
	v_mul_f32_e32 v77, v73, v73
	v_max_f32_e32 v73, v78, v78
	v_mul_f32_e32 v78, v74, v74
	v_max_f32_e32 v74, v79, v79
	v_max_f32_e32 v75, v75, v75
	v_lshl_add_u64 v[80:81], s[10:11], 0, v[80:81]
	v_max_f32_e32 v76, 0, v76
	v_mul_f32_e32 v72, v72, v72
	v_max_f32_e32 v73, 0, v73
	v_max_f32_e32 v74, 0, v74
	v_max_f32_e32 v75, 0, v75
	v_max_f32_e32 v64, v64, v64
	v_max_f32_e32 v65, v65, v65
	v_max_f32_e32 v66, v66, v66
	v_lshl_add_u64 v[80:81], v[80:81], 0, v[156:157]
	v_mul_f32_e32 v76, v76, v76
	v_mul_f32_e32 v73, v73, v73
	v_mul_f32_e32 v74, v74, v74
	v_mul_f32_e32 v75, v75, v75
	v_cvt_pk_bf16_f32 v72, v76, v72
	v_max_f32_e32 v64, 0, v64
	v_max_f32_e32 v65, 0, v65
	v_max_f32_e32 v66, 0, v66
	v_cvt_pk_bf16_f32 v73, v73, v74
	v_cvt_pk_bf16_f32 v74, v82, v77
	v_cvt_pk_bf16_f32 v75, v78, v75
	global_store_dwordx4 v[80:81], v[72:75], off
	v_max_f32_e32 v68, v68, v68
	v_max_f32_e32 v67, v67, v67
	v_mul_f32_e32 v72, v64, v64
	v_max_f32_e32 v64, v69, v69
	v_mul_f32_e32 v69, v65, v65
	v_max_f32_e32 v65, v70, v70
	v_mul_f32_e32 v70, v66, v66
	v_max_f32_e32 v66, v71, v71
	v_max_f32_e32 v64, 0, v64
	v_max_f32_e32 v65, 0, v65
	v_max_f32_e32 v66, 0, v66
	v_max_f32_e32 v68, 0, v68
	v_mul_f32_e32 v64, v64, v64
	v_mul_f32_e32 v65, v65, v65
	v_max_f32_e32 v67, 0, v67
	v_mul_f32_e32 v66, v66, v66
	v_max_f32_e32 v56, v56, v56
	v_mul_f32_e32 v68, v68, v68
	v_mul_f32_e32 v67, v67, v67
	v_cvt_pk_bf16_f32 v64, v68, v64
	v_cvt_pk_bf16_f32 v65, v65, v66
	v_cvt_pk_bf16_f32 v66, v72, v69
	v_max_f32_e32 v56, 0, v56
	v_max_f32_e32 v57, v57, v57
	v_max_f32_e32 v58, v58, v58
	v_cvt_pk_bf16_f32 v67, v70, v67
	global_store_dwordx4 v[80:81], v[64:67], off offset:256
	v_max_f32_e32 v60, v60, v60
	v_max_f32_e32 v57, 0, v57
	v_mul_f32_e32 v66, v56, v56
	v_max_f32_e32 v56, v61, v61
	v_max_f32_e32 v58, 0, v58
	v_max_f32_e32 v60, 0, v60
	v_max_f32_e32 v56, 0, v56
	v_mul_f32_e32 v61, v57, v57
; __device__ __forceinline__ unsigned cvt_pk_bf16(float lo, float hi) { unsigned r; asm volatile("v_cvt_pk_bf16_f32 %0, %1, %2" : "=v"(r) : "v"(lo), "v"(hi)); return r; }
;     __device__ __forceinline__ void operator()(const f32x4 (&acc)[2][2][4][2], const Unit& u, int ui, int wr, int wc, int fr, int fq) const {
;     ...
;             for (int m = 0; m < 4; ++m) { bf16_t* rowp = hid + (size_t)(row0 + ai * 128 + m * 16) * DFF + col0;
; #pragma unroll
;                 for (int bj = 0; bj < 2; ++bj) { f32x4 v0 = acc[ai][bj][m][0], v1 = acc[ai][bj][m][1];
; #pragma unroll
;                     for (int j = 0; j < 4; ++j) { const float a = fmaxf(v0[j], 0.f), b = fmaxf(v1[j], 0.f); v0[j] = a * a; v1[j] = b * b; }
;                     u32x4 w; w.x = cvt_pk_bf16(v0[0], v0[1]); w.y = cvt_pk_bf16(v0[2], v0[3]); w.z = cvt_pk_bf16(v1[0], v1[1]); w.w = cvt_pk_bf16(v1[2], v1[3]);
;                     *(u32x4*)(rowp + bj * 128) = w; } }
	v_max_f32_e32 v57, v62, v62
	v_mul_f32_e32 v62, v58, v58
	v_max_f32_e32 v58, v63, v63
	v_mul_f32_e32 v60, v60, v60
	v_mul_f32_e32 v56, v56, v56
	v_max_f32_e32 v57, 0, v57
	v_max_f32_e32 v58, 0, v58
	v_max_f32_e32 v59, v59, v59
	v_mul_f32_e32 v57, v57, v57
	v_max_f32_e32 v59, 0, v59
	v_mul_f32_e32 v58, v58, v58
	v_cvt_pk_bf16_f32 v56, v60, v56
	v_add_co_u32_e32 v60, vcc, s65, v144
	v_max_f32_e32 v48, v48, v48
	v_max_f32_e32 v49, v49, v49
	v_max_f32_e32 v50, v50, v50
	v_mul_f32_e32 v59, v59, v59
	v_cvt_pk_bf16_f32 v57, v57, v58
	v_cvt_pk_bf16_f32 v58, v66, v61
	v_addc_co_u32_e32 v61, vcc, 0, v145, vcc
	v_max_f32_e32 v48, 0, v48
	v_max_f32_e32 v49, 0, v49
	v_max_f32_e32 v50, 0, v50
	v_cvt_pk_bf16_f32 v59, v62, v59
	global_store_dwordx4 v[60:61], v[56:59], off
	v_max_f32_e32 v52, v52, v52
	v_max_f32_e32 v51, v51, v51
	v_mul_f32_e32 v56, v48, v48
	v_max_f32_e32 v48, v53, v53
	v_mul_f32_e32 v53, v49, v49
	v_max_f32_e32 v49, v54, v54
	v_mul_f32_e32 v54, v50, v50
	v_max_f32_e32 v50, v55, v55
	v_max_f32_e32 v48, 0, v48
	v_max_f32_e32 v49, 0, v49
	v_max_f32_e32 v50, 0, v50
	v_max_f32_e32 v52, 0, v52
	v_mul_f32_e32 v48, v48, v48
	v_mul_f32_e32 v49, v49, v49
	v_max_f32_e32 v51, 0, v51
	v_mul_f32_e32 v50, v50, v50
	v_max_f32_e32 v40, v40, v40
	v_lshl_add_u64 v[64:65], v[144:145], 0, s[14:15]
	v_mul_f32_e32 v52, v52, v52
	v_mul_f32_e32 v51, v51, v51
	v_cvt_pk_bf16_f32 v48, v52, v48
	v_cvt_pk_bf16_f32 v49, v49, v50
	v_cvt_pk_bf16_f32 v50, v56, v53
	v_max_f32_e32 v40, 0, v40
	v_max_f32_e32 v41, v41, v41
	v_max_f32_e32 v42, v42, v42
	v_cvt_pk_bf16_f32 v51, v54, v51
	global_store_dwordx4 v[64:65], v[48:51], off offset:256
	v_max_f32_e32 v44, v44, v44
	v_max_f32_e32 v41, 0, v41
	v_mul_f32_e32 v50, v40, v40
	v_max_f32_e32 v40, v45, v45
	v_max_f32_e32 v42, 0, v42
	v_max_f32_e32 v44, 0, v44
	v_max_f32_e32 v40, 0, v40
	v_mul_f32_e32 v45, v41, v41
	v_max_f32_e32 v41, v46, v46
	v_mul_f32_e32 v46, v42, v42
	v_max_f32_e32 v42, v47, v47
	v_mul_f32_e32 v44, v44, v44
	v_mul_f32_e32 v40, v40, v40
	v_max_f32_e32 v41, 0, v41
	v_max_f32_e32 v42, 0, v42
	v_max_f32_e32 v43, v43, v43
	v_mul_f32_e32 v41, v41, v41
	v_max_f32_e32 v43, 0, v43
	v_mul_f32_e32 v42, v42, v42
	v_cvt_pk_bf16_f32 v40, v44, v40
	v_add_co_u32_e32 v44, vcc, s66, v144
	v_max_f32_e32 v32, v32, v32
	v_max_f32_e32 v33, v33, v33
	v_max_f32_e32 v34, v34, v34
	v_mul_f32_e32 v43, v43, v43
	v_cvt_pk_bf16_f32 v41, v41, v42
	v_cvt_pk_bf16_f32 v42, v50, v45
	v_addc_co_u32_e32 v45, vcc, 0, v145, vcc
	v_max_f32_e32 v32, 0, v32
	v_max_f32_e32 v33, 0, v33
	v_max_f32_e32 v34, 0, v34
	v_cvt_pk_bf16_f32 v43, v46, v43
	global_store_dwordx4 v[44:45], v[40:43], off
	v_max_f32_e32 v36, v36, v36
	v_max_f32_e32 v35, v35, v35
	v_mul_f32_e32 v40, v32, v32
	v_max_f32_e32 v32, v37, v37
	v_mul_f32_e32 v37, v33, v33
	v_max_f32_e32 v33, v38, v38
	v_mul_f32_e32 v38, v34, v34
	v_max_f32_e32 v34, v39, v39
	v_max_f32_e32 v32, 0, v32
	v_max_f32_e32 v33, 0, v33
	v_max_f32_e32 v34, 0, v34
	v_max_f32_e32 v36, 0, v36
	v_mul_f32_e32 v32, v32, v32
	v_mul_f32_e32 v33, v33, v33
	v_max_f32_e32 v35, 0, v35
	v_mul_f32_e32 v34, v34, v34
	v_max_f32_e32 v24, v24, v24
	v_lshl_add_u64 v[48:49], v[144:145], 0, s[16:17]
	v_mul_f32_e32 v36, v36, v36
	v_mul_f32_e32 v35, v35, v35
	v_cvt_pk_bf16_f32 v32, v36, v32
	v_cvt_pk_bf16_f32 v33, v33, v34
	v_cvt_pk_bf16_f32 v34, v40, v37
	v_max_f32_e32 v24, 0, v24
	v_max_f32_e32 v25, v25, v25
	v_max_f32_e32 v26, v26, v26
	v_cvt_pk_bf16_f32 v35, v38, v35
	global_store_dwordx4 v[48:49], v[32:35], off offset:256
	v_max_f32_e32 v28, v28, v28
	v_max_f32_e32 v25, 0, v25
	v_mul_f32_e32 v34, v24, v24
	v_max_f32_e32 v24, v29, v29
; __device__ __forceinline__ unsigned cvt_pk_bf16(float lo, float hi) { unsigned r; asm volatile("v_cvt_pk_bf16_f32 %0, %1, %2" : "=v"(r) : "v"(lo), "v"(hi)); return r; }
; #define PG8_WAIT_V(n) asm volatile("s_waitcnt vmcnt(" #n ")" ::: "memory")
; #define PG8_BAR __builtin_amdgcn_s_barrier()
; template <class Epi, class Ptrs>
; __device__ __forceinline__ void gemm_phase(LAS unsigned char* lds, const int K, const StaticOrder& S, const Ptrs& P, const Epi& E) {
;     ...
;     PG8_WAIT_V(0);
;     if (wr == 0) PG8_BAR;
;     PG8_BAR;
;     __device__ __forceinline__ void operator()(const f32x4 (&acc)[2][2][4][2], const Unit& u, int ui, int wr, int wc, int fr, int fq) const {
;     ...
;             for (int m = 0; m < 4; ++m) { bf16_t* rowp = hid + (size_t)(row0 + ai * 128 + m * 16) * DFF + col0;
; #pragma unroll
;                 for (int bj = 0; bj < 2; ++bj) { f32x4 v0 = acc[ai][bj][m][0], v1 = acc[ai][bj][m][1];
; #pragma unroll
;                     for (int j = 0; j < 4; ++j) { const float a = fmaxf(v0[j], 0.f), b = fmaxf(v1[j], 0.f); v0[j] = a * a; v1[j] = b * b; }
;                     u32x4 w; w.x = cvt_pk_bf16(v0[0], v0[1]); w.y = cvt_pk_bf16(v0[2], v0[3]); w.z = cvt_pk_bf16(v1[0], v1[1]); w.w = cvt_pk_bf16(v1[2], v1[3]);
;                     *(u32x4*)(rowp + bj * 128) = w; } }
	v_max_f32_e32 v26, 0, v26
	v_max_f32_e32 v28, 0, v28
	v_max_f32_e32 v24, 0, v24
	v_mul_f32_e32 v29, v25, v25
	v_max_f32_e32 v25, v30, v30
	v_mul_f32_e32 v30, v26, v26
	v_max_f32_e32 v26, v31, v31
	v_mul_f32_e32 v28, v28, v28
	v_mul_f32_e32 v24, v24, v24
	v_max_f32_e32 v25, 0, v25
	v_max_f32_e32 v26, 0, v26
	v_max_f32_e32 v27, v27, v27
	v_mul_f32_e32 v25, v25, v25
	v_max_f32_e32 v27, 0, v27
	v_mul_f32_e32 v26, v26, v26
	v_cvt_pk_bf16_f32 v24, v28, v24
	v_add_co_u32_e32 v28, vcc, s67, v144
	v_max_f32_e32 v16, v16, v16
	v_max_f32_e32 v17, v17, v17
	v_max_f32_e32 v18, v18, v18
	v_mul_f32_e32 v27, v27, v27
	v_cvt_pk_bf16_f32 v25, v25, v26
	v_cvt_pk_bf16_f32 v26, v34, v29
	v_addc_co_u32_e32 v29, vcc, 0, v145, vcc
	v_max_f32_e32 v16, 0, v16
	v_max_f32_e32 v17, 0, v17
	v_max_f32_e32 v18, 0, v18
	v_cvt_pk_bf16_f32 v27, v30, v27
	global_store_dwordx4 v[28:29], v[24:27], off
	v_max_f32_e32 v20, v20, v20
	v_max_f32_e32 v19, v19, v19
	v_mul_f32_e32 v24, v16, v16
	v_max_f32_e32 v16, v21, v21
	v_mul_f32_e32 v21, v17, v17
	v_max_f32_e32 v17, v22, v22
	v_mul_f32_e32 v22, v18, v18
	v_max_f32_e32 v18, v23, v23
	v_max_f32_e32 v16, 0, v16
	v_max_f32_e32 v17, 0, v17
	v_max_f32_e32 v18, 0, v18
	v_max_f32_e32 v20, 0, v20
	v_mul_f32_e32 v16, v16, v16
	v_mul_f32_e32 v17, v17, v17
	v_max_f32_e32 v19, 0, v19
	v_mul_f32_e32 v18, v18, v18
	v_max_f32_e32 v8, v8, v8
	v_lshl_add_u64 v[32:33], v[144:145], 0, s[18:19]
	v_mul_f32_e32 v20, v20, v20
	v_mul_f32_e32 v19, v19, v19
	v_cvt_pk_bf16_f32 v16, v20, v16
	v_cvt_pk_bf16_f32 v17, v17, v18
	v_cvt_pk_bf16_f32 v18, v24, v21
	v_max_f32_e32 v8, 0, v8
	v_max_f32_e32 v9, v9, v9
	v_max_f32_e32 v10, v10, v10
	v_cvt_pk_bf16_f32 v19, v22, v19
	global_store_dwordx4 v[32:33], v[16:19], off offset:256
	v_max_f32_e32 v12, v12, v12
	v_max_f32_e32 v9, 0, v9
	v_mul_f32_e32 v18, v8, v8
	v_max_f32_e32 v8, v13, v13
	v_max_f32_e32 v10, 0, v10
	v_max_f32_e32 v12, 0, v12
	v_max_f32_e32 v8, 0, v8
	v_mul_f32_e32 v13, v9, v9
	v_max_f32_e32 v9, v14, v14
	v_mul_f32_e32 v14, v10, v10
	v_max_f32_e32 v10, v15, v15
	v_mul_f32_e32 v12, v12, v12
	v_mul_f32_e32 v8, v8, v8
	v_max_f32_e32 v9, 0, v9
	v_max_f32_e32 v10, 0, v10
	v_max_f32_e32 v11, v11, v11
	v_mul_f32_e32 v9, v9, v9
	v_max_f32_e32 v11, 0, v11
	v_mul_f32_e32 v10, v10, v10
	v_cvt_pk_bf16_f32 v8, v12, v8
	v_add_co_u32_e32 v12, vcc, s68, v144
	v_max_f32_e32 v0, v0, v0
	v_max_f32_e32 v1, v1, v1
	v_max_f32_e32 v2, v2, v2
	v_mul_f32_e32 v11, v11, v11
	v_cvt_pk_bf16_f32 v9, v9, v10
	v_cvt_pk_bf16_f32 v10, v18, v13
	v_addc_co_u32_e32 v13, vcc, 0, v145, vcc
	v_max_f32_e32 v0, 0, v0
	v_max_f32_e32 v1, 0, v1
	v_max_f32_e32 v2, 0, v2
	v_cvt_pk_bf16_f32 v11, v14, v11
	global_store_dwordx4 v[12:13], v[8:11], off
	v_max_f32_e32 v3, v3, v3
	v_max_f32_e32 v4, v4, v4
	v_mul_f32_e32 v8, v0, v0
	v_max_f32_e32 v0, v5, v5
	v_mul_f32_e32 v5, v1, v1
	v_max_f32_e32 v1, v6, v6
	v_mul_f32_e32 v6, v2, v2
	v_max_f32_e32 v2, v7, v7
	v_max_f32_e32 v0, 0, v0
	v_max_f32_e32 v1, 0, v1
	v_max_f32_e32 v2, 0, v2
	v_max_f32_e32 v3, 0, v3
	v_lshl_add_u64 v[16:17], v[144:145], 0, s[20:21]
	v_max_f32_e32 v4, 0, v4
	v_mul_f32_e32 v0, v0, v0
	v_mul_f32_e32 v1, v1, v1
	v_mul_f32_e32 v2, v2, v2
	v_mul_f32_e32 v3, v3, v3
	s_and_b64 vcc, exec, s[4:5]
	s_mov_b32 s69, s22
	s_mov_b32 s38, s24
	s_mov_b64 s[40:41], s[0:1]
	s_mov_b64 s[42:43], s[36:37]
	v_mul_f32_e32 v4, v4, v4
	v_cvt_pk_bf16_f32 v0, v4, v0
	v_cvt_pk_bf16_f32 v1, v1, v2
	v_cvt_pk_bf16_f32 v2, v8, v5
	v_cvt_pk_bf16_f32 v3, v6, v3
	global_store_dwordx4 v[16:17], v[0:3], off offset:256
	s_cbranch_vccz .LBB0_428
	s_waitcnt vmcnt(0)
	s_cmpk_gt_u32 s46, 0xff
	s_cbranch_scc1 .LBB0_437
	s_barrier

; #define PG8_STAGE(bufoff, gbase, voff) do { _Pragma("unroll") for (int _i = 0; _i < 2; ++_i) \
;         __builtin_amdgcn_global_load_lds((const unsigned*)((const char*)(gbase) + (voff)[_i]), (LAS unsigned*)(lds + (bufoff) + ldsw + _i * 8192), 16, 0, 0); } while (0)
; #define PG8_LDA(dst, b, h) do { _Pragma("unroll") for (int m = 0; m < 4; ++m) _Pragma("unroll") for (int k = 0; k < 2; ++k) dst[m][k] = *(const LAS bf16x8*)(lds + PG8_SA(b, h) + aoff + m * 2048 + k * 1024); } while (0)
; #define PG8_LDB(dst, b, h) do { _Pragma("unroll") for (int n = 0; n < 2; ++n) _Pragma("unroll") for (int k = 0; k < 2; ++k) dst[n][k] = *(const LAS bf16x8*)(lds + PG8_SB(b, h) + boff + n * 2048 + k * 1024); } while (0)
; #define PG8_MMA(ai, bj, At, Bt) do { __builtin_amdgcn_s_setprio(1); _Pragma("unroll") for (int m = 0; m < 4; ++m) _Pragma("unroll") for (int n = 0; n < 2; ++n) _Pragma("unroll") for (int k = 0; k < 2; ++k) \
;         acc[ai][bj][m][n] = __builtin_amdgcn_mfma_f32_16x16x32_bf16(Bt[n][k], At[m][k], acc[ai][bj][m][n], 0, 0, 0); __builtin_amdgcn_s_setprio(0); } while (0)
; #define PG8_WAIT_L(n) asm volatile("s_waitcnt lgkmcnt(" #n ")" ::: "memory")
; #define PG8_BAR __builtin_amdgcn_s_barrier()
; #define PG8_SCHED __builtin_amdgcn_sched_barrier(0)
; template <class Epi, class Ptrs>
; __device__ __forceinline__ void gemm_phase(LAS unsigned char* lds, const int K, const StaticOrder& S, const Ptrs& P, const Epi& E) {
;     ...
;             PG8_LDB(B0, 0, 0); PG8_SCHED; PG8_LDA(At, 0, 0); PG8_STAGE(PG8_SA(1, 1), a1 + hstep, voffA);
;             PG8_WAIT_L(8); PG8_BAR; PG8_WAIT_L(0); PG8_MMA(0, 0, At, B0); PG8_BAR; PG8_SCHED;
;             PG8_LDB(B1, 0, 1); PG8_STAGE(PG8_SB(0, 0), b2, voffB);
;             PG8_BAR; PG8_WAIT_L(0); PG8_MMA(0, 1, At, B1); PG8_BAR;
;             PG8_LDA(At, 0, 1); PG8_STAGE(PG8_SA(0, 0), a2, voffA);
;             PG8_BAR; PG8_WAIT_L(0); PG8_MMA(1, 0, At, B0); PG8_BAR; PG8_SCHED;
.LBB0_522:
	ds_read_b128 v[128:131], v193
	ds_read_b128 v[132:135], v193 offset:1024
	ds_read_b128 v[136:139], v193 offset:2048
	ds_read_b128 v[140:143], v193 offset:3072
	s_add_u32 s22, s20, 0xfff00080
	s_addc_u32 s23, s21, -1
	s_cmp_eq_u32 s46, 60
	s_cselect_b32 s25, s5, s23
	s_cselect_b32 s24, s4, s22
	s_cselect_b32 s23, s15, s13
	s_cselect_b32 s22, s14, s11
	v_lshl_add_u64 v[184:185], s[20:21], 0, v[168:169]
	s_add_i32 m0, s17, 0xc000
	ds_read_b128 v[144:147], v194
	ds_read_b128 v[148:151], v194 offset:1024
	ds_read_b128 v[152:155], v194 offset:2048
	ds_read_b128 v[156:159], v194 offset:3072
	ds_read_b128 v[176:179], v194 offset:4096
	ds_read_b128 v[180:183], v194 offset:5120
	ds_read_b128 v[196:199], v194 offset:6144
	ds_read_b128 v[200:203], v194 offset:7168
	global_load_lds_dwordx4 v[184:185], off
	v_lshl_add_u64 v[184:185], s[20:21], 0, v[170:171]
	s_add_i32 m0, s17, 0xe000
	s_nop 0
	global_load_lds_dwordx4 v[184:185], off
	s_waitcnt lgkmcnt(8)
	s_barrier
	s_waitcnt lgkmcnt(0)
	s_setprio 1
	s_waitcnt lgkmcnt(0)
	v_mfma_f32_16x16x32_bf16 v[124:127], v[128:131], v[144:147], v[124:127]
	v_mfma_f32_16x16x32_bf16 v[120:123], v[136:139], v[144:147], v[120:123]
	v_mfma_f32_16x16x32_bf16 v[104:107], v[136:139], v[152:155], v[104:107]
	v_mfma_f32_16x16x32_bf16 v[112:115], v[128:131], v[152:155], v[112:115]
	v_mfma_f32_16x16x32_bf16 v[92:95], v[128:131], v[176:179], v[92:95]
	v_mfma_f32_16x16x32_bf16 v[88:91], v[136:139], v[176:179], v[88:91]
	v_mfma_f32_16x16x32_bf16 v[72:75], v[136:139], v[196:199], v[72:75]
	v_mfma_f32_16x16x32_bf16 v[76:79], v[128:131], v[196:199], v[76:79]
	v_mfma_f32_16x16x32_bf16 v[124:127], v[132:135], v[148:151], v[124:127]
	v_mfma_f32_16x16x32_bf16 v[120:123], v[140:143], v[148:151], v[120:123]
	v_mfma_f32_16x16x32_bf16 v[104:107], v[140:143], v[156:159], v[104:107]
	v_mfma_f32_16x16x32_bf16 v[112:115], v[132:135], v[156:159], v[112:115]
	v_mfma_f32_16x16x32_bf16 v[92:95], v[132:135], v[180:183], v[92:95]
	v_mfma_f32_16x16x32_bf16 v[88:91], v[140:143], v[180:183], v[88:91]
	v_mfma_f32_16x16x32_bf16 v[72:75], v[140:143], v[200:203], v[72:75]
	v_mfma_f32_16x16x32_bf16 v[76:79], v[132:135], v[200:203], v[76:79]
	s_setprio 0
	s_barrier
	s_add_i32 s47, s42, s34
	v_lshl_add_u64 v[184:185], s[22:23], 0, v[162:163]
	s_mov_b32 m0, s47
	ds_read_b128 v[204:207], v195
	ds_read_b128 v[208:211], v195 offset:1024
	ds_read_b128 v[212:215], v195 offset:2048
	ds_read_b128 v[216:219], v195 offset:3072
	global_load_lds_dwordx4 v[184:185], off
	v_lshl_add_u64 v[220:221], s[22:23], 0, v[166:167]
	s_add_i32 m0, s47, 0x2000
	s_nop 0
	global_load_lds_dwordx4 v[220:221], off
	s_barrier
	s_waitcnt lgkmcnt(0)
	s_setprio 1
	s_waitcnt lgkmcnt(0)
	v_mfma_f32_16x16x32_bf16 v[116:119], v[204:207], v[144:147], v[116:119]
	v_mfma_f32_16x16x32_bf16 v[108:111], v[212:215], v[144:147], v[108:111]
	v_mfma_f32_16x16x32_bf16 v[96:99], v[212:215], v[152:155], v[96:99]
	v_mfma_f32_16x16x32_bf16 v[100:103], v[204:207], v[152:155], v[100:103]
	v_mfma_f32_16x16x32_bf16 v[84:87], v[204:207], v[176:179], v[84:87]
	v_mfma_f32_16x16x32_bf16 v[80:83], v[212:215], v[176:179], v[80:83]
	v_mfma_f32_16x16x32_bf16 v[64:67], v[212:215], v[196:199], v[64:67]
	v_mfma_f32_16x16x32_bf16 v[68:71], v[204:207], v[196:199], v[68:71]
	v_mfma_f32_16x16x32_bf16 v[116:119], v[208:211], v[148:151], v[116:119]
	v_mfma_f32_16x16x32_bf16 v[108:111], v[216:219], v[148:151], v[108:111]
	v_mfma_f32_16x16x32_bf16 v[96:99], v[216:219], v[156:159], v[96:99]
	v_mfma_f32_16x16x32_bf16 v[100:103], v[208:211], v[156:159], v[100:103]
	v_mfma_f32_16x16x32_bf16 v[84:87], v[208:211], v[180:183], v[84:87]
	v_mfma_f32_16x16x32_bf16 v[80:83], v[216:219], v[180:183], v[80:83]
	v_mfma_f32_16x16x32_bf16 v[64:67], v[216:219], v[200:203], v[64:67]
	v_mfma_f32_16x16x32_bf16 v[68:71], v[208:211], v[200:203], v[68:71]
	s_setprio 0
	s_mov_b32 m0, s17
	v_lshl_add_u64 v[222:223], s[24:25], 0, v[160:161]
	s_barrier
	ds_read_b128 v[144:147], v194 offset:16384
	ds_read_b128 v[148:151], v194 offset:17408
	ds_read_b128 v[152:155], v194 offset:18432
	ds_read_b128 v[156:159], v194 offset:19456
	ds_read_b128 v[176:179], v194 offset:20480
	ds_read_b128 v[180:183], v194 offset:21504
	ds_read_b128 v[196:199], v194 offset:22528
	ds_read_b128 v[200:203], v194 offset:23552
	global_load_lds_dwordx4 v[222:223], off
	v_lshl_add_u64 v[224:225], s[24:25], 0, v[164:165]
	s_mov_b32 m0, s19
	s_nop 0
	global_load_lds_dwordx4 v[224:225], off
	s_barrier
	s_waitcnt lgkmcnt(0)
	s_setprio 1
	s_waitcnt lgkmcnt(0)
	v_mfma_f32_16x16x32_bf16 v[60:63], v[128:131], v[144:147], v[60:63]
	v_mfma_f32_16x16x32_bf16 v[56:59], v[136:139], v[144:147], v[56:59]
	v_mfma_f32_16x16x32_bf16 v[40:43], v[136:139], v[152:155], v[40:43]
	v_mfma_f32_16x16x32_bf16 v[48:51], v[128:131], v[152:155], v[48:51]
	v_mfma_f32_16x16x32_bf16 v[32:35], v[128:131], v[176:179], v[32:35]
	v_mfma_f32_16x16x32_bf16 v[24:27], v[136:139], v[176:179], v[24:27]
	v_mfma_f32_16x16x32_bf16 v[8:11], v[136:139], v[196:199], v[8:11]
	v_mfma_f32_16x16x32_bf16 v[16:19], v[128:131], v[196:199], v[16:19]
	v_mfma_f32_16x16x32_bf16 v[60:63], v[132:135], v[148:151], v[60:63]
	v_mfma_f32_16x16x32_bf16 v[56:59], v[140:143], v[148:151], v[56:59]
	v_mfma_f32_16x16x32_bf16 v[40:43], v[140:143], v[156:159], v[40:43]
	v_mfma_f32_16x16x32_bf16 v[48:51], v[132:135], v[156:159], v[48:51]
	v_mfma_f32_16x16x32_bf16 v[32:35], v[132:135], v[180:183], v[32:35]
	v_mfma_f32_16x16x32_bf16 v[24:27], v[140:143], v[180:183], v[24:27]
	v_mfma_f32_16x16x32_bf16 v[8:11], v[140:143], v[200:203], v[8:11]
	v_mfma_f32_16x16x32_bf16 v[16:19], v[132:135], v[200:203], v[16:19]
	s_setprio 0
	s_barrier
; #define PG8_STAGE(bufoff, gbase, voff) do { _Pragma("unroll") for (int _i = 0; _i < 2; ++_i) \
;         __builtin_amdgcn_global_load_lds((const unsigned*)((const char*)(gbase) + (voff)[_i]), (LAS unsigned*)(lds + (bufoff) + ldsw + _i * 8192), 16, 0, 0); } while (0)
; #define PG8_LDA(dst, b, h) do { _Pragma("unroll") for (int m = 0; m < 4; ++m) _Pragma("unroll") for (int k = 0; k < 2; ++k) dst[m][k] = *(const LAS bf16x8*)(lds + PG8_SA(b, h) + aoff + m * 2048 + k * 1024); } while (0)
; #define PG8_LDB(dst, b, h) do { _Pragma("unroll") for (int n = 0; n < 2; ++n) _Pragma("unroll") for (int k = 0; k < 2; ++k) dst[n][k] = *(const LAS bf16x8*)(lds + PG8_SB(b, h) + boff + n * 2048 + k * 1024); } while (0)
; #define PG8_MMA(ai, bj, At, Bt) do { __builtin_amdgcn_s_setprio(1); _Pragma("unroll") for (int m = 0; m < 4; ++m) _Pragma("unroll") for (int n = 0; n < 2; ++n) _Pragma("unroll") for (int k = 0; k < 2; ++k) \
;         acc[ai][bj][m][n] = __builtin_amdgcn_mfma_f32_16x16x32_bf16(Bt[n][k], At[m][k], acc[ai][bj][m][n], 0, 0, 0); __builtin_amdgcn_s_setprio(0); } while (0)
; #define PG8_WAIT_V(n) asm volatile("s_waitcnt vmcnt(" #n ")" ::: "memory")
; #define PG8_WAIT_L(n) asm volatile("s_waitcnt lgkmcnt(" #n ")" ::: "memory")
; #define PG8_BAR __builtin_amdgcn_s_barrier()
; #define PG8_SCHED __builtin_amdgcn_sched_barrier(0)
; template <class Epi, class Ptrs>
; __device__ __forceinline__ void gemm_phase(LAS unsigned char* lds, const int K, const StaticOrder& S, const Ptrs& P, const Epi& E) {
;     ...
;             PG8_STAGE(PG8_SB(0, 1), b2 + hstep, voffB);
;             PG8_WAIT_V(6); PG8_BAR; PG8_MMA(1, 1, At, B1); PG8_BAR;
;             PG8_LDB(B0, 1, 0); PG8_SCHED; PG8_LDA(At, 1, 0); PG8_STAGE(PG8_SA(0, 1), a2 + hstep, voffA);
;             PG8_WAIT_L(8); PG8_BAR; PG8_WAIT_L(0); PG8_MMA(0, 0, At, B0); PG8_BAR; PG8_SCHED;
;             PG8_LDB(B1, 1, 1); PG8_STAGE(PG8_SB(1, 0), b3, voffB);
;             PG8_BAR; PG8_WAIT_L(0); PG8_MMA(0, 1, At, B1); PG8_BAR;
;             PG8_LDA(At, 1, 1); PG8_STAGE(PG8_SA(1, 0), a3, voffA);
	s_add_u32 s48, s22, 0x100000
	s_addc_u32 s49, s23, 0
	s_add_i32 s47, s43, s34
	v_lshl_add_u64 v[128:129], s[48:49], 0, v[162:163]
	s_mov_b32 m0, s47
	s_nop 0
	global_load_lds_dwordx4 v[128:129], off
	v_lshl_add_u64 v[128:129], s[48:49], 0, v[166:167]
	s_add_i32 m0, s47, 0x2000
	s_nop 0
	global_load_lds_dwordx4 v[128:129], off
	s_waitcnt vmcnt(6)
	s_barrier
	s_setprio 1
	v_mfma_f32_16x16x32_bf16 v[52:55], v[204:207], v[144:147], v[52:55]
	v_mfma_f32_16x16x32_bf16 v[44:47], v[212:215], v[144:147], v[44:47]
	v_mfma_f32_16x16x32_bf16 v[28:31], v[212:215], v[152:155], v[28:31]
	v_mfma_f32_16x16x32_bf16 v[36:39], v[204:207], v[152:155], v[36:39]
	v_mfma_f32_16x16x32_bf16 v[20:23], v[204:207], v[176:179], v[20:23]
	v_mfma_f32_16x16x32_bf16 v[12:15], v[212:215], v[176:179], v[12:15]
	v_mfma_f32_16x16x32_bf16 v[0:3], v[212:215], v[196:199], v[0:3]
	v_mfma_f32_16x16x32_bf16 v[4:7], v[204:207], v[196:199], v[4:7]
	v_mfma_f32_16x16x32_bf16 v[52:55], v[208:211], v[148:151], v[52:55]
	v_mfma_f32_16x16x32_bf16 v[44:47], v[216:219], v[148:151], v[44:47]
	v_mfma_f32_16x16x32_bf16 v[28:31], v[216:219], v[156:159], v[28:31]
	v_mfma_f32_16x16x32_bf16 v[36:39], v[208:211], v[156:159], v[36:39]
	v_mfma_f32_16x16x32_bf16 v[20:23], v[208:211], v[180:183], v[20:23]
	v_mfma_f32_16x16x32_bf16 v[12:15], v[216:219], v[180:183], v[12:15]
	v_mfma_f32_16x16x32_bf16 v[0:3], v[216:219], v[200:203], v[0:3]
	v_mfma_f32_16x16x32_bf16 v[4:7], v[208:211], v[200:203], v[4:7]
	s_setprio 0
	s_add_i32 s47, 0, 0x18000
	v_add_u32_e32 v140, s47, v187
	s_barrier
	ds_read_b128 v[128:131], v140
	ds_read_b128 v[132:135], v140 offset:1024
	ds_read_b128 v[136:139], v140 offset:2048
	ds_read_b128 v[140:143], v140 offset:3072
	s_add_u32 s24, s24, 0x100000
	s_addc_u32 s25, s25, 0
	s_mov_b32 m0, s40
	v_lshl_add_u64 v[204:205], s[24:25], 0, v[160:161]
	ds_read_b128 v[144:147], v194 offset:32768
	ds_read_b128 v[148:151], v194 offset:33792
	ds_read_b128 v[152:155], v194 offset:34816
	ds_read_b128 v[156:159], v194 offset:35840
	ds_read_b128 v[176:179], v194 offset:36864
	ds_read_b128 v[180:183], v194 offset:37888
	ds_read_b128 v[196:199], v194 offset:38912
	ds_read_b128 v[200:203], v194 offset:39936
	global_load_lds_dwordx4 v[204:205], off
	v_lshl_add_u64 v[204:205], s[24:25], 0, v[164:165]
	s_mov_b32 m0, s41
	s_nop 0
	global_load_lds_dwordx4 v[204:205], off
	s_waitcnt lgkmcnt(8)
	s_barrier
	s_waitcnt lgkmcnt(0)
	s_setprio 1
	s_waitcnt lgkmcnt(0)
	v_mfma_f32_16x16x32_bf16 v[124:127], v[128:131], v[144:147], v[124:127]
	v_mfma_f32_16x16x32_bf16 v[120:123], v[136:139], v[144:147], v[120:123]
	v_mfma_f32_16x16x32_bf16 v[104:107], v[136:139], v[152:155], v[104:107]
	v_mfma_f32_16x16x32_bf16 v[112:115], v[128:131], v[152:155], v[112:115]
	v_mfma_f32_16x16x32_bf16 v[92:95], v[128:131], v[176:179], v[92:95]
	v_mfma_f32_16x16x32_bf16 v[88:91], v[136:139], v[176:179], v[88:91]
	v_mfma_f32_16x16x32_bf16 v[72:75], v[136:139], v[196:199], v[72:75]
	v_mfma_f32_16x16x32_bf16 v[76:79], v[128:131], v[196:199], v[76:79]
	v_mfma_f32_16x16x32_bf16 v[124:127], v[132:135], v[148:151], v[124:127]
	v_mfma_f32_16x16x32_bf16 v[120:123], v[140:143], v[148:151], v[120:123]
	v_mfma_f32_16x16x32_bf16 v[104:107], v[140:143], v[156:159], v[104:107]
	v_mfma_f32_16x16x32_bf16 v[112:115], v[132:135], v[156:159], v[112:115]
	v_mfma_f32_16x16x32_bf16 v[92:95], v[132:135], v[180:183], v[92:95]
	v_mfma_f32_16x16x32_bf16 v[88:91], v[140:143], v[180:183], v[88:91]
	v_mfma_f32_16x16x32_bf16 v[72:75], v[140:143], v[200:203], v[72:75]
	v_mfma_f32_16x16x32_bf16 v[76:79], v[132:135], v[200:203], v[76:79]
	s_setprio 0
	s_barrier
	s_add_i32 s24, 0, 0x1c000
	s_add_i32 s25, s47, s34
	v_add_u32_e32 v216, s24, v187
	v_lshl_add_u64 v[184:185], v[184:185], 0, s[8:9]
	s_mov_b32 m0, s25
	ds_read_b128 v[204:207], v216
	ds_read_b128 v[208:211], v216 offset:1024
	ds_read_b128 v[212:215], v216 offset:2048
	ds_read_b128 v[216:219], v216 offset:3072
	global_load_lds_dwordx4 v[184:185], off
	v_lshl_add_u64 v[184:185], v[220:221], 0, s[8:9]
	s_add_i32 m0, s25, 0x2000
	s_nop 0
	global_load_lds_dwordx4 v[184:185], off
	s_barrier
	s_waitcnt lgkmcnt(0)
	s_setprio 1
	s_waitcnt lgkmcnt(0)
	v_mfma_f32_16x16x32_bf16 v[116:119], v[204:207], v[144:147], v[116:119]
	v_mfma_f32_16x16x32_bf16 v[108:111], v[212:215], v[144:147], v[108:111]
	v_mfma_f32_16x16x32_bf16 v[96:99], v[212:215], v[152:155], v[96:99]
	v_mfma_f32_16x16x32_bf16 v[100:103], v[204:207], v[152:155], v[100:103]
	v_mfma_f32_16x16x32_bf16 v[84:87], v[204:207], v[176:179], v[84:87]
	v_mfma_f32_16x16x32_bf16 v[80:83], v[212:215], v[176:179], v[80:83]
	v_mfma_f32_16x16x32_bf16 v[64:67], v[212:215], v[196:199], v[64:67]
	v_mfma_f32_16x16x32_bf16 v[68:71], v[204:207], v[196:199], v[68:71]
	v_mfma_f32_16x16x32_bf16 v[116:119], v[208:211], v[148:151], v[116:119]
	v_mfma_f32_16x16x32_bf16 v[108:111], v[216:219], v[148:151], v[108:111]
	v_mfma_f32_16x16x32_bf16 v[96:99], v[216:219], v[156:159], v[96:99]
	v_mfma_f32_16x16x32_bf16 v[100:103], v[208:211], v[156:159], v[100:103]
	v_mfma_f32_16x16x32_bf16 v[84:87], v[208:211], v[180:183], v[84:87]
	v_mfma_f32_16x16x32_bf16 v[80:83], v[216:219], v[180:183], v[80:83]
	v_mfma_f32_16x16x32_bf16 v[64:67], v[216:219], v[200:203], v[64:67]
	v_mfma_f32_16x16x32_bf16 v[68:71], v[208:211], v[200:203], v[68:71]
	s_setprio 0
	s_mov_b32 m0, s28
	v_lshl_add_u64 v[184:185], v[222:223], 0, s[8:9]
	s_barrier
	ds_read_b128 v[144:147], v194 offset:49152
	ds_read_b128 v[148:151], v194 offset:50176
	ds_read_b128 v[152:155], v194 offset:51200
	ds_read_b128 v[156:159], v194 offset:52224
	ds_read_b128 v[176:179], v194 offset:53248
	ds_read_b128 v[180:183], v194 offset:54272
	ds_read_b128 v[196:199], v194 offset:55296
	ds_read_b128 v[200:203], v194 offset:56320
	global_load_lds_dwordx4 v[184:185], off
	v_lshl_add_u64 v[184:185], v[224:225], 0, s[8:9]
	s_mov_b32 m0, s29
	s_nop 0
	global_load_lds_dwordx4 v[184:185], off
	s_barrier
; #define PG8_STAGE(bufoff, gbase, voff) do { _Pragma("unroll") for (int _i = 0; _i < 2; ++_i) \
;         __builtin_amdgcn_global_load_lds((const unsigned*)((const char*)(gbase) + (voff)[_i]), (LAS unsigned*)(lds + (bufoff) + ldsw + _i * 8192), 16, 0, 0); } while (0)
; #define PG8_MMA(ai, bj, At, Bt) do { __builtin_amdgcn_s_setprio(1); _Pragma("unroll") for (int m = 0; m < 4; ++m) _Pragma("unroll") for (int n = 0; n < 2; ++n) _Pragma("unroll") for (int k = 0; k < 2; ++k) \
;         acc[ai][bj][m][n] = __builtin_amdgcn_mfma_f32_16x16x32_bf16(Bt[n][k], At[m][k], acc[ai][bj][m][n], 0, 0, 0); __builtin_amdgcn_s_setprio(0); } while (0)
; #define PG8_WAIT_V(n) asm volatile("s_waitcnt vmcnt(" #n ")" ::: "memory")
; #define PG8_WAIT_L(n) asm volatile("s_waitcnt lgkmcnt(" #n ")" ::: "memory")
; #define PG8_BAR __builtin_amdgcn_s_barrier()
; #define PG8_SCHED __builtin_amdgcn_sched_barrier(0)
; template <class Epi, class Ptrs>
; __device__ __forceinline__ void gemm_phase(LAS unsigned char* lds, const int K, const StaticOrder& S, const Ptrs& P, const Epi& E) {
;     ...
;             PG8_BAR; PG8_WAIT_L(0); PG8_MMA(1, 0, At, B0); PG8_BAR; PG8_SCHED;
;             PG8_STAGE(PG8_SB(1, 1), b3 + hstep, voffB);
;             PG8_WAIT_V(6); PG8_BAR; PG8_MMA(1, 1, At, B1); PG8_BAR;
;     __device__ __forceinline__ void operator()(const f32x4 (&acc)[2][2][4][2], const Unit& u, int ui, int wr, int wc, int fr, int fq) const {
;     ...
;         u32x4 xv[2][4][2];
; #pragma unroll
;         for (int ai = 0; ai < 2; ++ai)
; #pragma unroll
;             for (int m = 0; m < 4; ++m)
; #pragma unroll
;                 for (int bj = 0; bj < 2; ++bj) xv[ai][m][bj] = *(const u32x4*)(xb + (size_t)(u.pm * 256 + rl0 + ai * 128 + m * 16) * DM + col0 + bj * 128);
; #pragma unroll
;         for (int ai = 0; ai < 2; ++ai)
; #pragma unroll
;             for (int m = 0; m < 4; ++m) { const int rl = rl0 + ai * 128 + m * 16; float* rowp = out + (size_t)(u.pm * 256 + rl) * DM + col0;
;                 const float r2 = tab[ui * 256 + rl];
	s_waitcnt lgkmcnt(0)
	s_setprio 1
	s_waitcnt lgkmcnt(0)
	v_mfma_f32_16x16x32_bf16 v[60:63], v[128:131], v[144:147], v[60:63]
	v_mfma_f32_16x16x32_bf16 v[56:59], v[136:139], v[144:147], v[56:59]
	v_mfma_f32_16x16x32_bf16 v[40:43], v[136:139], v[152:155], v[40:43]
	v_mfma_f32_16x16x32_bf16 v[48:51], v[128:131], v[152:155], v[48:51]
	v_mfma_f32_16x16x32_bf16 v[32:35], v[128:131], v[176:179], v[32:35]
	v_mfma_f32_16x16x32_bf16 v[24:27], v[136:139], v[176:179], v[24:27]
	v_mfma_f32_16x16x32_bf16 v[8:11], v[136:139], v[196:199], v[8:11]
	v_mfma_f32_16x16x32_bf16 v[16:19], v[128:131], v[196:199], v[16:19]
	v_mfma_f32_16x16x32_bf16 v[60:63], v[132:135], v[148:151], v[60:63]
	v_mfma_f32_16x16x32_bf16 v[56:59], v[140:143], v[148:151], v[56:59]
	v_mfma_f32_16x16x32_bf16 v[40:43], v[140:143], v[156:159], v[40:43]
	v_mfma_f32_16x16x32_bf16 v[48:51], v[132:135], v[156:159], v[48:51]
	v_mfma_f32_16x16x32_bf16 v[32:35], v[132:135], v[180:183], v[32:35]
	v_mfma_f32_16x16x32_bf16 v[24:27], v[140:143], v[180:183], v[24:27]
	v_mfma_f32_16x16x32_bf16 v[8:11], v[140:143], v[200:203], v[8:11]
	v_mfma_f32_16x16x32_bf16 v[16:19], v[132:135], v[200:203], v[16:19]
	s_setprio 0
	s_barrier
	s_add_u32 s22, s22, 0x100080
	s_addc_u32 s23, s23, 0
	s_add_i32 s24, s24, s34
	v_lshl_add_u64 v[128:129], s[22:23], 0, v[162:163]
	s_mov_b32 m0, s24
	s_nop 0
	global_load_lds_dwordx4 v[128:129], off
	v_lshl_add_u64 v[128:129], s[22:23], 0, v[166:167]
	s_add_i32 m0, s24, 0x2000
	s_nop 0
	global_load_lds_dwordx4 v[128:129], off
	s_waitcnt vmcnt(6)
	s_barrier
	s_setprio 1
	v_mfma_f32_16x16x32_bf16 v[52:55], v[204:207], v[144:147], v[52:55]
	v_mfma_f32_16x16x32_bf16 v[44:47], v[212:215], v[144:147], v[44:47]
	v_mfma_f32_16x16x32_bf16 v[28:31], v[212:215], v[152:155], v[28:31]
	v_mfma_f32_16x16x32_bf16 v[36:39], v[204:207], v[152:155], v[36:39]
	v_mfma_f32_16x16x32_bf16 v[20:23], v[204:207], v[176:179], v[20:23]
	v_mfma_f32_16x16x32_bf16 v[12:15], v[212:215], v[176:179], v[12:15]
	v_mfma_f32_16x16x32_bf16 v[0:3], v[212:215], v[196:199], v[0:3]
	v_mfma_f32_16x16x32_bf16 v[4:7], v[204:207], v[196:199], v[4:7]
	v_mfma_f32_16x16x32_bf16 v[52:55], v[208:211], v[148:151], v[52:55]
	v_mfma_f32_16x16x32_bf16 v[44:47], v[216:219], v[148:151], v[44:47]
	v_mfma_f32_16x16x32_bf16 v[28:31], v[216:219], v[156:159], v[28:31]
	v_mfma_f32_16x16x32_bf16 v[36:39], v[208:211], v[156:159], v[36:39]
	v_mfma_f32_16x16x32_bf16 v[20:23], v[208:211], v[180:183], v[20:23]
	v_mfma_f32_16x16x32_bf16 v[12:15], v[216:219], v[180:183], v[12:15]
	v_mfma_f32_16x16x32_bf16 v[0:3], v[216:219], v[200:203], v[0:3]
	v_mfma_f32_16x16x32_bf16 v[4:7], v[208:211], v[200:203], v[4:7]
	s_setprio 0
	s_add_i32 s46, s46, 2
	s_add_u32 s20, s20, 0x100
	s_addc_u32 s21, s21, 0
	s_add_u32 s11, s11, 0x100
	s_addc_u32 s13, s13, 0
	s_cmp_gt_u32 s46, 61
	s_barrier
	s_cbranch_scc0 .LBB0_522
	s_lshl_b32 s11, s18, 8
	v_lshl_or_b32 v128, s16, 8, v191
	v_add_u32_e32 v130, s11, v186
	v_ashrrev_i32_e32 v129, 31, v128
	v_ashrrev_i32_e32 v131, 31, v130
	v_lshl_add_u64 v[132:133], v[128:129], 1, s[6:7]
	v_lshlrev_b64 v[134:135], 11, v[130:131]
	v_lshl_add_u64 v[134:135], v[132:133], 0, v[134:135]
	global_load_dwordx4 v[198:201], v[134:135], off
	global_load_dwordx4 v[202:205], v[134:135], off offset:256
	v_or_b32_e32 v134, 16, v130
	v_ashrrev_i32_e32 v135, 31, v134
	v_lshlrev_b64 v[134:135], 11, v[134:135]
	v_lshl_add_u64 v[134:135], v[132:133], 0, v[134:135]
	global_load_dwordx4 v[206:209], v[134:135], off
	global_load_dwordx4 v[210:213], v[134:135], off offset:256
	v_or_b32_e32 v136, 32, v130
	v_ashrrev_i32_e32 v137, 31, v136
	v_or_b32_e32 v138, 48, v130
	v_add_u32_e32 v184, 0x80, v130
	v_add_u32_e32 v182, 0x90, v130
	v_add_u32_e32 v180, 0xa0, v130
	v_add_u32_e32 v178, 0xb0, v130
	v_lshlrev_b64 v[176:177], 2, v[128:129]
	v_lshlrev_b64 v[128:129], 12, v[130:131]
	v_lshlrev_b64 v[130:131], 11, v[136:137]
	v_lshl_add_u64 v[130:131], v[132:133], 0, v[130:131]
	global_load_dwordx4 v[214:217], v[130:131], off
	v_ashrrev_i32_e32 v139, 31, v138
	v_ashrrev_i32_e32 v185, 31, v184
	v_ashrrev_i32_e32 v183, 31, v182
	v_ashrrev_i32_e32 v181, 31, v180
	v_ashrrev_i32_e32 v179, 31, v178
	v_lshlrev_b64 v[134:135], 11, v[138:139]
	v_lshlrev_b64 v[136:137], 11, v[184:185]
	v_lshlrev_b64 v[138:139], 11, v[182:183]
	v_lshl_add_u32 v196, s45, 10, v192
	v_lshlrev_b64 v[140:141], 11, v[180:181]
	v_lshlrev_b64 v[142:143], 11, v[178:179]
	v_lshl_add_u64 v[128:129], s[26:27], 0, v[128:129]
	v_lshl_add_u64 v[134:135], v[132:133], 0, v[134:135]
	v_lshl_add_u64 v[136:137], v[132:133], 0, v[136:137]
	v_lshl_add_u64 v[138:139], v[132:133], 0, v[138:139]
	ds_read2_b32 v[230:231], v196 offset1:16
	v_lshl_add_u64 v[234:235], v[132:133], 0, v[140:141]
	v_lshl_add_u64 v[236:237], v[132:133], 0, v[142:143]
	v_lshl_add_u64 v[238:239], v[128:129], 0, v[176:177]
	global_load_dwordx4 v[218:221], v[130:131], off offset:256
	global_load_dwordx4 v[222:225], v[134:135], off
	global_load_dwordx4 v[226:229], v[134:135], off offset:256
	global_load_dwordx4 v[156:159], v[136:137], off
	global_load_dwordx4 v[152:155], v[136:137], off offset:256
	global_load_dwordx4 v[148:151], v[138:139], off
	global_load_dwordx4 v[144:147], v[138:139], off offset:256
	global_load_dwordx4 v[140:143], v[234:235], off
	s_nop 0
	global_load_dwordx4 v[136:139], v[234:235], off offset:256
	global_load_dwordx4 v[132:135], v[236:237], off
	global_load_dwordx4 v[128:131], v[236:237], off offset:256
	v_add_u32_e32 v232, s11, v188
	v_ashrrev_i32_e32 v233, 31, v232
	s_and_b64 vcc, exec, s[0:1]
	s_mov_b32 s16, s10
	s_mov_b32 s18, s12
	s_mov_b64 s[20:21], s[4:5]
	s_mov_b64 s[22:23], s[14:15]
	s_mov_b32 s45, s44
	s_waitcnt vmcnt(0)
; __device__ __forceinline__ float bf_lo(unsigned w) { return __uint_as_float(w << 16); }
; __device__ __forceinline__ float bf_hi(unsigned w) { return __uint_as_float(w & 0xffff0000u); }
;     __device__ __forceinline__ void operator()(const f32x4 (&acc)[2][2][4][2], const Unit& u, int ui, int wr, int wc, int fr, int fq) const {
;     ...
;         for (int ai = 0; ai < 2; ++ai)
; #pragma unroll
;             for (int m = 0; m < 4; ++m) { const int rl = rl0 + ai * 128 + m * 16; float* rowp = out + (size_t)(u.pm * 256 + rl) * DM + col0;
;                 const float r2 = tab[ui * 256 + rl];
; #pragma unroll
;                 for (int bj = 0; bj < 2; ++bj) { const u32x4 x = xv[ai][m][bj];
;                     const f32x4 x0 = {bf_lo(x.x), bf_hi(x.x), bf_lo(x.y), bf_hi(x.y)}, x1 = {bf_lo(x.z), bf_hi(x.z), bf_lo(x.w), bf_hi(x.w)};
;                     *(f32x4*)(rowp + bj * 128) = acc[ai][bj][m][0] * r2 + x0; *(f32x4*)(rowp + bj * 128 + 4) = acc[ai][bj][m][1] * r2 + x1; } }
	v_lshlrev_b32_e32 v234, 16, v198
	v_and_b32_e32 v235, 0xffff0000, v198
	v_lshlrev_b32_e32 v198, 16, v199
	v_and_b32_e32 v199, 0xffff0000, v199
	v_lshlrev_b32_e32 v242, 16, v204
	v_and_b32_e32 v243, 0xffff0000, v204
	v_lshlrev_b32_e32 v236, 16, v200
	v_and_b32_e32 v237, 0xffff0000, v200
	v_lshlrev_b32_e32 v200, 16, v201
	v_and_b32_e32 v201, 0xffff0000, v201
	v_lshlrev_b32_e32 v240, 16, v202
	v_and_b32_e32 v241, 0xffff0000, v202
	v_lshlrev_b32_e32 v202, 16, v203
	v_and_b32_e32 v203, 0xffff0000, v203
	v_lshlrev_b32_e32 v204, 16, v205
	v_and_b32_e32 v205, 0xffff0000, v205
	s_waitcnt lgkmcnt(0)
	v_pk_fma_f32 v[126:127], v[126:127], v[230:231], v[198:199] op_sel_hi:[1,0,1]
	v_pk_fma_f32 v[124:125], v[124:125], v[230:231], v[234:235] op_sel_hi:[1,0,1]
	v_pk_fma_f32 v[108:109], v[108:109], v[230:231], v[242:243] op_sel_hi:[1,0,1]
	v_pk_fma_f32 v[122:123], v[122:123], v[230:231], v[200:201] op_sel_hi:[1,0,1]
	v_pk_fma_f32 v[120:121], v[120:121], v[230:231], v[236:237] op_sel_hi:[1,0,1]
	v_pk_fma_f32 v[118:119], v[118:119], v[230:231], v[202:203] op_sel_hi:[1,0,1]
	v_pk_fma_f32 v[116:117], v[116:117], v[230:231], v[240:241] op_sel_hi:[1,0,1]
	v_pk_fma_f32 v[110:111], v[110:111], v[230:231], v[204:205] op_sel_hi:[1,0,1]
	global_store_dwordx4 v[238:239], v[124:127], off
	global_store_dwordx4 v[238:239], v[120:123], off offset:16
	global_store_dwordx4 v[238:239], v[116:119], off offset:512
	global_store_dwordx4 v[238:239], v[108:111], off offset:528
	v_mov_b32_e32 v122, v231
	v_lshlrev_b32_e32 v118, 16, v208
	v_lshlrev_b64 v[108:109], 12, v[232:233]
	v_lshl_add_u64 v[108:109], s[26:27], 0, v[108:109]
	v_lshl_add_u64 v[116:117], v[108:109], 0, v[176:177]
	v_lshlrev_b32_e32 v108, 16, v206
	v_and_b32_e32 v109, 0xffff0000, v206
	v_lshlrev_b32_e32 v110, 16, v207
	v_and_b32_e32 v111, 0xffff0000, v207
	v_pk_fma_f32 v[110:111], v[114:115], v[122:123], v[110:111] op_sel_hi:[1,0,1]
	v_pk_fma_f32 v[108:109], v[112:113], v[122:123], v[108:109] op_sel_hi:[1,0,1]
	global_store_dwordx4 v[116:117], v[108:111], off
	v_and_b32_e32 v119, 0xffff0000, v208
	v_lshlrev_b32_e32 v120, 16, v209
	v_lshlrev_b32_e32 v108, 16, v212
	v_and_b32_e32 v109, 0xffff0000, v212
	v_lshlrev_b32_e32 v110, 16, v213
	v_and_b32_e32 v111, 0xffff0000, v213
	v_pk_fma_f32 v[98:99], v[98:99], v[122:123], v[110:111] op_sel_hi:[1,0,1]
	v_pk_fma_f32 v[96:97], v[96:97], v[122:123], v[108:109] op_sel_hi:[1,0,1]
	v_and_b32_e32 v121, 0xffff0000, v209
	global_store_dwordx4 v[116:117], v[96:99], off offset:528
	ds_read2_b32 v[98:99], v196 offset0:32 offset1:48
	v_pk_fma_f32 v[106:107], v[106:107], v[122:123], v[120:121] op_sel_hi:[1,0,1]
	v_pk_fma_f32 v[104:105], v[104:105], v[122:123], v[118:119] op_sel_hi:[1,0,1]
	v_add_u32_e32 v96, s11, v189
	global_store_dwordx4 v[116:117], v[104:107], off offset:16
	v_ashrrev_i32_e32 v97, 31, v96
	v_lshlrev_b64 v[96:97], 12, v[96:97]
	v_lshlrev_b32_e32 v104, 16, v210
	v_and_b32_e32 v105, 0xffff0000, v210
	v_lshlrev_b32_e32 v106, 16, v211
	v_and_b32_e32 v107, 0xffff0000, v211
	v_pk_fma_f32 v[102:103], v[102:103], v[122:123], v[106:107] op_sel_hi:[1,0,1]
	v_pk_fma_f32 v[100:101], v[100:101], v[122:123], v[104:105] op_sel_hi:[1,0,1]
	global_store_dwordx4 v[116:117], v[100:103], off offset:512
	v_lshl_add_u64 v[96:97], s[26:27], 0, v[96:97]
	v_lshl_add_u64 v[96:97], v[96:97], 0, v[176:177]
	v_lshlrev_b32_e32 v100, 16, v214
	v_and_b32_e32 v101, 0xffff0000, v214
	v_lshlrev_b32_e32 v102, 16, v215
	v_and_b32_e32 v103, 0xffff0000, v215
	s_waitcnt lgkmcnt(0)
	v_pk_fma_f32 v[94:95], v[94:95], v[98:99], v[102:103] op_sel_hi:[1,0,1]
	v_pk_fma_f32 v[92:93], v[92:93], v[98:99], v[100:101] op_sel_hi:[1,0,1]
	global_store_dwordx4 v[96:97], v[92:95], off
	v_lshlrev_b32_e32 v104, 16, v216
	v_and_b32_e32 v105, 0xffff0000, v216
	v_lshlrev_b32_e32 v92, 16, v220
	v_and_b32_e32 v93, 0xffff0000, v220
	v_lshlrev_b32_e32 v94, 16, v221
	v_and_b32_e32 v95, 0xffff0000, v221
	v_lshlrev_b32_e32 v106, 16, v217
	v_and_b32_e32 v107, 0xffff0000, v217
	v_pk_fma_f32 v[82:83], v[82:83], v[98:99], v[94:95] op_sel_hi:[1,0,1]
	v_pk_fma_f32 v[80:81], v[80:81], v[98:99], v[92:93] op_sel_hi:[1,0,1]
	v_pk_fma_f32 v[90:91], v[90:91], v[98:99], v[106:107] op_sel_hi:[1,0,1]
	v_pk_fma_f32 v[88:89], v[88:89], v[98:99], v[104:105] op_sel_hi:[1,0,1]
	global_store_dwordx4 v[96:97], v[80:83], off offset:528
	global_store_dwordx4 v[96:97], v[88:91], off offset:16
	s_nop 0
	v_add_u32_e32 v80, s11, v190
	v_lshlrev_b32_e32 v88, 16, v218
	v_and_b32_e32 v89, 0xffff0000, v218
	v_lshlrev_b32_e32 v90, 16, v219
	v_and_b32_e32 v91, 0xffff0000, v219
	v_ashrrev_i32_e32 v81, 31, v80
	v_pk_fma_f32 v[86:87], v[86:87], v[98:99], v[90:91] op_sel_hi:[1,0,1]
	v_pk_fma_f32 v[84:85], v[84:85], v[98:99], v[88:89] op_sel_hi:[1,0,1]
	v_lshlrev_b64 v[80:81], 12, v[80:81]
	global_store_dwordx4 v[96:97], v[84:87], off offset:512
	v_lshl_add_u64 v[80:81], s[26:27], 0, v[80:81]
	v_lshlrev_b32_e32 v82, 16, v222
	v_and_b32_e32 v83, 0xffff0000, v222
	v_lshlrev_b32_e32 v84, 16, v223
	v_and_b32_e32 v85, 0xffff0000, v223
	v_mov_b32_e32 v90, v99
	v_lshl_add_u64 v[80:81], v[80:81], 0, v[176:177]
	v_pk_fma_f32 v[78:79], v[78:79], v[90:91], v[84:85] op_sel_hi:[1,0,1]
	v_pk_fma_f32 v[76:77], v[76:77], v[90:91], v[82:83] op_sel_hi:[1,0,1]
	global_store_dwordx4 v[80:81], v[76:79], off
	v_lshlrev_b32_e32 v86, 16, v224
	v_and_b32_e32 v87, 0xffff0000, v224
	v_lshlrev_b32_e32 v76, 16, v228
	v_and_b32_e32 v77, 0xffff0000, v228
	v_lshlrev_b32_e32 v78, 16, v229
	v_and_b32_e32 v79, 0xffff0000, v229
	v_pk_fma_f32 v[66:67], v[66:67], v[90:91], v[78:79] op_sel_hi:[1,0,1]
	v_pk_fma_f32 v[64:65], v[64:65], v[90:91], v[76:77] op_sel_hi:[1,0,1]
	v_lshlrev_b32_e32 v88, 16, v225
	v_and_b32_e32 v89, 0xffff0000, v225
	global_store_dwordx4 v[80:81], v[64:67], off offset:528
	ds_read2_b32 v[66:67], v196 offset0:128 offset1:144
	v_pk_fma_f32 v[74:75], v[74:75], v[90:91], v[88:89] op_sel_hi:[1,0,1]
	v_pk_fma_f32 v[72:73], v[72:73], v[90:91], v[86:87] op_sel_hi:[1,0,1]
	global_store_dwordx4 v[80:81], v[72:75], off offset:16
	v_lshlrev_b64 v[64:65], 12, v[184:185]
	v_lshl_add_u64 v[64:65], s[26:27], 0, v[64:65]
	v_lshlrev_b32_e32 v72, 16, v226
	v_and_b32_e32 v73, 0xffff0000, v226
	v_lshlrev_b32_e32 v74, 16, v227
	v_and_b32_e32 v75, 0xffff0000, v227
	v_pk_fma_f32 v[70:71], v[70:71], v[90:91], v[74:75] op_sel_hi:[1,0,1]
	v_pk_fma_f32 v[68:69], v[68:69], v[90:91], v[72:73] op_sel_hi:[1,0,1]
	global_store_dwordx4 v[80:81], v[68:71], off offset:512
	v_lshl_add_u64 v[64:65], v[64:65], 0, v[176:177]
	v_lshlrev_b32_e32 v72, 16, v158
	v_lshlrev_b32_e32 v68, 16, v156
	v_and_b32_e32 v69, 0xffff0000, v156
	v_lshlrev_b32_e32 v70, 16, v157
	v_and_b32_e32 v71, 0xffff0000, v157
	v_and_b32_e32 v73, 0xffff0000, v158
	v_lshlrev_b32_e32 v74, 16, v159
	v_and_b32_e32 v75, 0xffff0000, v159
	s_waitcnt lgkmcnt(0)
; __device__ __forceinline__ float bf_lo(unsigned w) { return __uint_as_float(w << 16); }
; __device__ __forceinline__ float bf_hi(unsigned w) { return __uint_as_float(w & 0xffff0000u); }
; #define PG8_WAIT_V(n) asm volatile("s_waitcnt vmcnt(" #n ")" ::: "memory")
; #define PG8_BAR __builtin_amdgcn_s_barrier()
; template <class Epi, class Ptrs>
; __device__ __forceinline__ void gemm_phase(LAS unsigned char* lds, const int K, const StaticOrder& S, const Ptrs& P, const Epi& E) {
;     ...
;     PG8_WAIT_V(0);
;     if (wr == 0) PG8_BAR;
;     PG8_BAR;
;     __device__ __forceinline__ void operator()(const f32x4 (&acc)[2][2][4][2], const Unit& u, int ui, int wr, int wc, int fr, int fq) const {
;     ...
;         for (int ai = 0; ai < 2; ++ai)
; #pragma unroll
;             for (int m = 0; m < 4; ++m) { const int rl = rl0 + ai * 128 + m * 16; float* rowp = out + (size_t)(u.pm * 256 + rl) * DM + col0;
;                 const float r2 = tab[ui * 256 + rl];
; #pragma unroll
;                 for (int bj = 0; bj < 2; ++bj) { const u32x4 x = xv[ai][m][bj];
;                     const f32x4 x0 = {bf_lo(x.x), bf_hi(x.x), bf_lo(x.y), bf_hi(x.y)}, x1 = {bf_lo(x.z), bf_hi(x.z), bf_lo(x.w), bf_hi(x.w)};
;                     *(f32x4*)(rowp + bj * 128) = acc[ai][bj][m][0] * r2 + x0; *(f32x4*)(rowp + bj * 128 + 4) = acc[ai][bj][m][1] * r2 + x1; } }
	v_pk_fma_f32 v[62:63], v[62:63], v[66:67], v[70:71] op_sel_hi:[1,0,1]
	v_pk_fma_f32 v[60:61], v[60:61], v[66:67], v[68:69] op_sel_hi:[1,0,1]
	global_store_dwordx4 v[64:65], v[60:63], off
	v_pk_fma_f32 v[58:59], v[58:59], v[66:67], v[74:75] op_sel_hi:[1,0,1]
	v_pk_fma_f32 v[56:57], v[56:57], v[66:67], v[72:73] op_sel_hi:[1,0,1]
	v_lshlrev_b32_e32 v60, 16, v154
	v_and_b32_e32 v61, 0xffff0000, v154
	v_lshlrev_b32_e32 v62, 16, v155
	v_and_b32_e32 v63, 0xffff0000, v155
	global_store_dwordx4 v[64:65], v[56:59], off offset:16
	v_pk_fma_f32 v[46:47], v[46:47], v[66:67], v[62:63] op_sel_hi:[1,0,1]
	v_pk_fma_f32 v[44:45], v[44:45], v[66:67], v[60:61] op_sel_hi:[1,0,1]
	v_lshlrev_b32_e32 v56, 16, v152
	v_and_b32_e32 v57, 0xffff0000, v152
	v_lshlrev_b32_e32 v58, 16, v153
	v_and_b32_e32 v59, 0xffff0000, v153
	v_pk_fma_f32 v[54:55], v[54:55], v[66:67], v[58:59] op_sel_hi:[1,0,1]
	v_pk_fma_f32 v[52:53], v[52:53], v[66:67], v[56:57] op_sel_hi:[1,0,1]
	global_store_dwordx4 v[64:65], v[44:47], off offset:528
	global_store_dwordx4 v[64:65], v[52:55], off offset:512
	v_lshlrev_b32_e32 v56, 16, v151
	v_lshlrev_b64 v[44:45], 12, v[182:183]
	v_lshl_add_u64 v[44:45], s[26:27], 0, v[44:45]
	v_lshlrev_b32_e32 v54, 16, v150
	v_and_b32_e32 v55, 0xffff0000, v150
	v_and_b32_e32 v57, 0xffff0000, v151
	v_mov_b32_e32 v58, v67
	v_lshl_add_u64 v[52:53], v[44:45], 0, v[176:177]
	v_pk_fma_f32 v[42:43], v[42:43], v[58:59], v[56:57] op_sel_hi:[1,0,1]
	v_pk_fma_f32 v[40:41], v[40:41], v[58:59], v[54:55] op_sel_hi:[1,0,1]
	v_lshlrev_b32_e32 v44, 16, v148
	v_and_b32_e32 v45, 0xffff0000, v148
	v_lshlrev_b32_e32 v46, 16, v149
	v_and_b32_e32 v47, 0xffff0000, v149
	global_store_dwordx4 v[52:53], v[40:43], off offset:16
	v_pk_fma_f32 v[46:47], v[50:51], v[58:59], v[46:47] op_sel_hi:[1,0,1]
	v_pk_fma_f32 v[44:45], v[48:49], v[58:59], v[44:45] op_sel_hi:[1,0,1]
	v_lshlrev_b32_e32 v40, 16, v144
	v_and_b32_e32 v41, 0xffff0000, v144
	v_lshlrev_b32_e32 v42, 16, v145
	v_and_b32_e32 v43, 0xffff0000, v145
	v_pk_fma_f32 v[38:39], v[38:39], v[58:59], v[42:43] op_sel_hi:[1,0,1]
	v_pk_fma_f32 v[36:37], v[36:37], v[58:59], v[40:41] op_sel_hi:[1,0,1]
	global_store_dwordx4 v[52:53], v[44:47], off
	global_store_dwordx4 v[52:53], v[36:39], off offset:512
	ds_read2_b32 v[38:39], v196 offset0:160 offset1:176
	v_lshlrev_b32_e32 v44, 16, v146
	v_and_b32_e32 v45, 0xffff0000, v146
	v_lshlrev_b32_e32 v46, 16, v147
	v_and_b32_e32 v47, 0xffff0000, v147
	v_pk_fma_f32 v[30:31], v[30:31], v[58:59], v[46:47] op_sel_hi:[1,0,1]
	v_pk_fma_f32 v[28:29], v[28:29], v[58:59], v[44:45] op_sel_hi:[1,0,1]
	global_store_dwordx4 v[52:53], v[28:31], off offset:528
	v_lshlrev_b32_e32 v40, 16, v142
	v_and_b32_e32 v41, 0xffff0000, v142
	v_lshlrev_b64 v[28:29], 12, v[180:181]
	v_lshl_add_u64 v[28:29], s[26:27], 0, v[28:29]
	v_lshl_add_u64 v[36:37], v[28:29], 0, v[176:177]
	v_lshlrev_b32_e32 v28, 16, v140
	v_and_b32_e32 v29, 0xffff0000, v140
	v_lshlrev_b32_e32 v30, 16, v141
	v_and_b32_e32 v31, 0xffff0000, v141
	s_waitcnt lgkmcnt(0)
	v_pk_fma_f32 v[30:31], v[34:35], v[38:39], v[30:31] op_sel_hi:[1,0,1]
	v_pk_fma_f32 v[28:29], v[32:33], v[38:39], v[28:29] op_sel_hi:[1,0,1]
	v_lshlrev_b32_e32 v42, 16, v143
	v_and_b32_e32 v43, 0xffff0000, v143
	global_store_dwordx4 v[36:37], v[28:31], off
	v_pk_fma_f32 v[26:27], v[26:27], v[38:39], v[42:43] op_sel_hi:[1,0,1]
	v_pk_fma_f32 v[24:25], v[24:25], v[38:39], v[40:41] op_sel_hi:[1,0,1]
	v_lshlrev_b32_e32 v28, 16, v138
	v_and_b32_e32 v29, 0xffff0000, v138
	v_lshlrev_b32_e32 v30, 16, v139
	v_and_b32_e32 v31, 0xffff0000, v139
	v_pk_fma_f32 v[14:15], v[14:15], v[38:39], v[30:31] op_sel_hi:[1,0,1]
	v_pk_fma_f32 v[12:13], v[12:13], v[38:39], v[28:29] op_sel_hi:[1,0,1]
	global_store_dwordx4 v[36:37], v[24:27], off offset:16
	global_store_dwordx4 v[36:37], v[12:15], off offset:528
	s_nop 0
	v_lshlrev_b32_e32 v24, 16, v136
	v_and_b32_e32 v25, 0xffff0000, v136
	v_lshlrev_b32_e32 v26, 16, v137
	v_and_b32_e32 v27, 0xffff0000, v137
	v_lshlrev_b64 v[12:13], 12, v[178:179]
	v_pk_fma_f32 v[22:23], v[22:23], v[38:39], v[26:27] op_sel_hi:[1,0,1]
	v_pk_fma_f32 v[20:21], v[20:21], v[38:39], v[24:25] op_sel_hi:[1,0,1]
	v_lshl_add_u64 v[12:13], s[26:27], 0, v[12:13]
	global_store_dwordx4 v[36:37], v[20:23], off offset:512
	v_lshlrev_b32_e32 v14, 16, v133
	v_and_b32_e32 v15, 0xffff0000, v133
	v_lshl_add_u64 v[20:21], v[12:13], 0, v[176:177]
	v_lshlrev_b32_e32 v12, 16, v132
	v_and_b32_e32 v13, 0xffff0000, v132
	v_lshlrev_b32_e32 v22, 16, v134
	v_and_b32_e32 v23, 0xffff0000, v134
	v_lshlrev_b32_e32 v24, 16, v135
	v_and_b32_e32 v25, 0xffff0000, v135
	v_mov_b32_e32 v26, v39
	v_pk_fma_f32 v[14:15], v[18:19], v[26:27], v[14:15] op_sel_hi:[1,0,1]
	v_pk_fma_f32 v[12:13], v[16:17], v[26:27], v[12:13] op_sel_hi:[1,0,1]
	v_pk_fma_f32 v[10:11], v[10:11], v[26:27], v[24:25] op_sel_hi:[1,0,1]
	v_pk_fma_f32 v[8:9], v[8:9], v[26:27], v[22:23] op_sel_hi:[1,0,1]
	global_store_dwordx4 v[20:21], v[12:15], off
	global_store_dwordx4 v[20:21], v[8:11], off offset:16
	s_nop 0
	v_lshlrev_b32_e32 v12, 16, v130
	v_lshlrev_b32_e32 v8, 16, v128
	v_and_b32_e32 v9, 0xffff0000, v128
	v_lshlrev_b32_e32 v10, 16, v129
	v_and_b32_e32 v11, 0xffff0000, v129
	v_and_b32_e32 v13, 0xffff0000, v130
	v_lshlrev_b32_e32 v14, 16, v131
	v_and_b32_e32 v15, 0xffff0000, v131
	v_pk_fma_f32 v[6:7], v[6:7], v[26:27], v[10:11] op_sel_hi:[1,0,1]
	v_pk_fma_f32 v[4:5], v[4:5], v[26:27], v[8:9] op_sel_hi:[1,0,1]
	v_pk_fma_f32 v[2:3], v[2:3], v[26:27], v[14:15] op_sel_hi:[1,0,1]
	v_pk_fma_f32 v[0:1], v[0:1], v[26:27], v[12:13] op_sel_hi:[1,0,1]
	global_store_dwordx4 v[20:21], v[4:7], off offset:512
	global_store_dwordx4 v[20:21], v[0:3], off offset:528
	s_cbranch_vccz .LBB0_517
	s_waitcnt vmcnt(0)
	s_cmpk_gt_u32 s33, 0xff
	s_cbranch_scc1 .LBB0_526
	s_barrier
